# v30 plus the score-row loads at the default cache policy too
# baseline (speedup 1.0000x reference)
.LBB0_803:
	s_or_b32 s4, s1, s19
	s_add_i32 s3, s22, s1
	s_ashr_i32 s5, s4, 31
	s_add_i32 s74, s3, 1
	s_lshl_b64 s[4:5], s[4:5], 15
	v_and_b32_e32 v30, 63, v0
	s_add_u32 s4, s86, s4
	s_addc_u32 s5, s87, s5
	v_ashrrev_i32_e32 v31, 31, v30
	v_lshl_add_u64 v[2:3], v[30:31], 2, s[4:5]
	s_cmpk_gt_i32 s3, 0xff
	s_mov_b64 s[4:5], -1
	s_cbranch_scc0 .LBB0_2181
	s_cmpk_lt_u32 s3, 0x3ff
	s_mov_b64 s[6:7], -1
	s_cbranch_scc1 .LBB0_808
	global_load_dword v19, v[2:3], off
	global_load_dword v13, v[2:3], off offset:256
	global_load_dword v20, v[2:3], off offset:512
	global_load_dword v12, v[2:3], off offset:768
	global_load_dword v18, v[2:3], off offset:1024
	global_load_dword v10, v[2:3], off offset:1280
	global_load_dword v17, v[2:3], off offset:1536
	global_load_dword v9, v[2:3], off offset:1792
	global_load_dword v16, v[2:3], off offset:2048
	global_load_dword v8, v[2:3], off offset:2304
	global_load_dword v15, v[2:3], off offset:2560
	global_load_dword v7, v[2:3], off offset:2816
	global_load_dword v14, v[2:3], off offset:3072
	global_load_dword v5, v[2:3], off offset:3328
	global_load_dword v11, v[2:3], off offset:3584
	global_load_dword v4, v[2:3], off offset:3840
	s_cbranch_execz .LBB0_809

.LBB0_807:
	v_add_co_u32_e32 v38, vcc, 0x1000, v2
	s_nop 1
	v_addc_co_u32_e32 v39, vcc, 0, v3, vcc
	global_load_dword v22, v[38:39], off
	global_load_dword v21, v[38:39], off offset:256
	global_load_dword v24, v[38:39], off offset:512
	global_load_dword v23, v[38:39], off offset:768
	global_load_dword v26, v[38:39], off offset:1024
	global_load_dword v25, v[38:39], off offset:1280
	global_load_dword v28, v[38:39], off offset:1536
	global_load_dword v27, v[38:39], off offset:1792
	global_load_dword v31, v[38:39], off offset:2048
	global_load_dword v29, v[38:39], off offset:2304
	global_load_dword v33, v[38:39], off offset:2560
	global_load_dword v32, v[38:39], off offset:2816
	global_load_dword v35, v[38:39], off offset:3072
	global_load_dword v34, v[38:39], off offset:3328
	global_load_dword v37, v[38:39], off offset:3584
	global_load_dword v36, v[38:39], off offset:3840
	s_cbranch_execnz .LBB0_877
	s_branch .LBB0_843

.LBB0_809:
	v_mov_b32_e32 v21, v30
	v_mov_b32_e32 v13, 0
	v_cmp_ge_i32_e32 vcc, s3, v21
	v_mov_b32_e32 v19, 0
	s_and_saveexec_b64 s[4:5], vcc
	s_cbranch_execz .LBB0_811
	global_load_dword v19, v[2:3], off
.LBB0_811:
	s_or_b64 exec, exec, s[4:5]
	v_add_u32_e32 v4, 64, v21
	v_cmp_ge_i32_e32 vcc, s3, v4
	s_and_saveexec_b64 s[4:5], vcc
	s_cbranch_execz .LBB0_813
	global_load_dword v13, v[2:3], off offset:256
.LBB0_813:
	s_or_b64 exec, exec, s[4:5]
	v_add_u32_e32 v4, 0x80, v21
	v_cmp_ge_i32_e32 vcc, s3, v4
	v_mov_b32_e32 v12, 0
	v_mov_b32_e32 v20, 0
	s_and_saveexec_b64 s[4:5], vcc
	s_cbranch_execz .LBB0_815
	global_load_dword v20, v[2:3], off offset:512
.LBB0_815:
	s_or_b64 exec, exec, s[4:5]
	v_add_u32_e32 v4, 0xc0, v21
	v_cmp_ge_i32_e32 vcc, s3, v4
	s_and_saveexec_b64 s[4:5], vcc
	s_cbranch_execz .LBB0_817
	global_load_dword v12, v[2:3], off offset:768
.LBB0_817:
	s_or_b64 exec, exec, s[4:5]
	v_add_u32_e32 v4, 0x100, v21
	v_cmp_ge_i32_e32 vcc, s3, v4
	v_mov_b32_e32 v10, 0
	v_mov_b32_e32 v18, 0
	s_and_saveexec_b64 s[4:5], vcc
	s_cbranch_execz .LBB0_819
	global_load_dword v18, v[2:3], off offset:1024
.LBB0_819:
	s_or_b64 exec, exec, s[4:5]
	v_add_u32_e32 v4, 0x140, v21
	v_cmp_ge_i32_e32 vcc, s3, v4
	s_and_saveexec_b64 s[4:5], vcc
	s_cbranch_execz .LBB0_821
	global_load_dword v10, v[2:3], off offset:1280
.LBB0_821:
	s_or_b64 exec, exec, s[4:5]
	v_add_u32_e32 v4, 0x180, v21
	v_cmp_ge_i32_e32 vcc, s3, v4
	v_mov_b32_e32 v9, 0
	v_mov_b32_e32 v17, 0
	s_and_saveexec_b64 s[4:5], vcc
	s_cbranch_execz .LBB0_823
	global_load_dword v17, v[2:3], off offset:1536
.LBB0_823:
	s_or_b64 exec, exec, s[4:5]
	v_add_u32_e32 v4, 0x1c0, v21
	v_cmp_ge_i32_e32 vcc, s3, v4
	s_and_saveexec_b64 s[4:5], vcc
	s_cbranch_execz .LBB0_825
	global_load_dword v9, v[2:3], off offset:1792
.LBB0_825:
	s_or_b64 exec, exec, s[4:5]
	v_add_u32_e32 v4, 0x200, v21
	v_cmp_ge_i32_e32 vcc, s3, v4
	v_mov_b32_e32 v8, 0
	v_mov_b32_e32 v16, 0
	s_and_saveexec_b64 s[4:5], vcc
	s_cbranch_execz .LBB0_827
	global_load_dword v16, v[2:3], off offset:2048
.LBB0_827:
	s_or_b64 exec, exec, s[4:5]
	v_add_u32_e32 v4, 0x240, v21
	v_cmp_ge_i32_e32 vcc, s3, v4
	s_and_saveexec_b64 s[4:5], vcc
	s_cbranch_execz .LBB0_829
	global_load_dword v8, v[2:3], off offset:2304
.LBB0_829:
	s_or_b64 exec, exec, s[4:5]
	v_add_u32_e32 v4, 0x280, v21
	v_cmp_ge_i32_e32 vcc, s3, v4
	v_mov_b32_e32 v7, 0
	v_mov_b32_e32 v15, 0
	s_and_saveexec_b64 s[4:5], vcc
	s_cbranch_execz .LBB0_831
	global_load_dword v15, v[2:3], off offset:2560
.LBB0_831:
	s_or_b64 exec, exec, s[4:5]
	v_add_u32_e32 v4, 0x2c0, v21
	v_cmp_ge_i32_e32 vcc, s3, v4
	s_and_saveexec_b64 s[4:5], vcc
	s_cbranch_execz .LBB0_833
	global_load_dword v7, v[2:3], off offset:2816
.LBB0_833:
	s_or_b64 exec, exec, s[4:5]
	v_add_u32_e32 v4, 0x300, v21
	v_cmp_ge_i32_e32 vcc, s3, v4
	v_mov_b32_e32 v5, 0
	v_mov_b32_e32 v14, 0
	s_and_saveexec_b64 s[4:5], vcc
	s_cbranch_execz .LBB0_835
	global_load_dword v14, v[2:3], off offset:3072
.LBB0_835:
	s_or_b64 exec, exec, s[4:5]
	v_add_u32_e32 v4, 0x340, v21
	v_cmp_ge_i32_e32 vcc, s3, v4
	s_and_saveexec_b64 s[4:5], vcc
	s_cbranch_execz .LBB0_837
	global_load_dword v5, v[2:3], off offset:3328
.LBB0_837:
	s_or_b64 exec, exec, s[4:5]
	v_add_u32_e32 v4, 0x380, v21
	v_cmp_ge_i32_e32 vcc, s3, v4
	v_mov_b32_e32 v4, 0
	v_mov_b32_e32 v11, 0
	s_and_saveexec_b64 s[4:5], vcc
	s_cbranch_execz .LBB0_839
	global_load_dword v11, v[2:3], off offset:3584
.LBB0_839:
	s_or_b64 exec, exec, s[4:5]
	v_add_u32_e32 v21, 0x3c0, v21
	v_cmp_ge_i32_e32 vcc, s3, v21
	s_and_saveexec_b64 s[4:5], vcc
	s_cbranch_execz .LBB0_841
	global_load_dword v4, v[2:3], off offset:3840

.LBB0_843:
	v_mov_b32_e32 v22, 0
	s_cmpk_lt_u32 s3, 0x400
	v_mov_b32_e32 v21, 0
	v_mov_b32_e32 v24, 0
	v_mov_b32_e32 v23, 0
	v_mov_b32_e32 v26, 0
	v_mov_b32_e32 v25, 0
	v_mov_b32_e32 v28, 0
	v_mov_b32_e32 v27, 0
	v_mov_b32_e32 v31, 0
	v_mov_b32_e32 v29, 0
	v_mov_b32_e32 v33, 0
	v_mov_b32_e32 v32, 0
	v_mov_b32_e32 v35, 0
	v_mov_b32_e32 v34, 0
	v_mov_b32_e32 v37, 0
	v_mov_b32_e32 v36, 0
	s_cbranch_scc1 .LBB0_877
	v_mov_b32_e32 v38, v30
	v_mov_b32_e32 v22, 0
	v_add_u32_e32 v21, 0x400, v38
	v_cmp_ge_i32_e32 vcc, s3, v21
	v_mov_b32_e32 v21, 0
	s_and_saveexec_b64 s[6:7], vcc
	s_cbranch_execz .LBB0_846
	v_add_co_u32_e32 v22, vcc, 0x1000, v2
	s_nop 1
	v_addc_co_u32_e32 v23, vcc, 0, v3, vcc
	global_load_dword v22, v[22:23], off
.LBB0_846:
	s_or_b64 exec, exec, s[6:7]
	v_add_u32_e32 v23, 0x440, v38
	v_cmp_ge_i32_e32 vcc, s3, v23
	s_and_saveexec_b64 s[6:7], vcc
	s_cbranch_execz .LBB0_848
	v_add_co_u32_e32 v24, vcc, 0x1000, v2
	s_nop 1
	v_addc_co_u32_e32 v25, vcc, 0, v3, vcc
	global_load_dword v21, v[24:25], off offset:256
.LBB0_848:
	s_or_b64 exec, exec, s[6:7]
	v_add_u32_e32 v23, 0x480, v38
	v_cmp_ge_i32_e32 vcc, s3, v23
	v_mov_b32_e32 v23, 0
	v_mov_b32_e32 v24, 0
	s_and_saveexec_b64 s[6:7], vcc
	s_cbranch_execz .LBB0_850
	v_add_co_u32_e32 v24, vcc, 0x1000, v2
	s_nop 1
	v_addc_co_u32_e32 v25, vcc, 0, v3, vcc
	global_load_dword v24, v[24:25], off offset:512
.LBB0_850:
	s_or_b64 exec, exec, s[6:7]
	v_add_u32_e32 v25, 0x4c0, v38
	v_cmp_ge_i32_e32 vcc, s3, v25
	s_and_saveexec_b64 s[6:7], vcc
	s_cbranch_execz .LBB0_852
	v_add_co_u32_e32 v26, vcc, 0x1000, v2
	s_nop 1
	v_addc_co_u32_e32 v27, vcc, 0, v3, vcc
	global_load_dword v23, v[26:27], off offset:768
.LBB0_852:
	s_or_b64 exec, exec, s[6:7]
	v_add_u32_e32 v25, 0x500, v38
	v_cmp_ge_i32_e32 vcc, s3, v25
	v_mov_b32_e32 v25, 0
	v_mov_b32_e32 v26, 0
	s_and_saveexec_b64 s[6:7], vcc
	s_cbranch_execz .LBB0_854
	v_add_co_u32_e32 v26, vcc, 0x1000, v2
	s_nop 1
	v_addc_co_u32_e32 v27, vcc, 0, v3, vcc
	global_load_dword v26, v[26:27], off offset:1024
.LBB0_854:
	s_or_b64 exec, exec, s[6:7]
	v_add_u32_e32 v27, 0x540, v38
	v_cmp_ge_i32_e32 vcc, s3, v27
	s_and_saveexec_b64 s[6:7], vcc
	s_cbranch_execz .LBB0_856
	v_add_co_u32_e32 v28, vcc, 0x1000, v2
	s_nop 1
	v_addc_co_u32_e32 v29, vcc, 0, v3, vcc
	global_load_dword v25, v[28:29], off offset:1280
.LBB0_856:
	s_or_b64 exec, exec, s[6:7]
	v_add_u32_e32 v27, 0x580, v38
	v_cmp_ge_i32_e32 vcc, s3, v27
	v_mov_b32_e32 v27, 0
	v_mov_b32_e32 v28, 0
	s_and_saveexec_b64 s[6:7], vcc
	s_cbranch_execz .LBB0_858
	v_add_co_u32_e32 v28, vcc, 0x1000, v2
	s_nop 1
	v_addc_co_u32_e32 v29, vcc, 0, v3, vcc
	global_load_dword v28, v[28:29], off offset:1536
.LBB0_858:
	s_or_b64 exec, exec, s[6:7]
	v_add_u32_e32 v29, 0x5c0, v38
	v_cmp_ge_i32_e32 vcc, s3, v29
	s_and_saveexec_b64 s[6:7], vcc
	s_cbranch_execz .LBB0_860
	v_add_co_u32_e32 v32, vcc, 0x1000, v2
	s_nop 1
	v_addc_co_u32_e32 v33, vcc, 0, v3, vcc
	global_load_dword v27, v[32:33], off offset:1792
.LBB0_860:
	s_or_b64 exec, exec, s[6:7]
	v_add_u32_e32 v29, 0x600, v38
	v_cmp_ge_i32_e32 vcc, s3, v29
	v_mov_b32_e32 v29, 0
	v_mov_b32_e32 v31, 0
	s_and_saveexec_b64 s[6:7], vcc
	s_cbranch_execz .LBB0_862
	v_add_co_u32_e32 v32, vcc, 0x1000, v2
	s_nop 1
	v_addc_co_u32_e32 v33, vcc, 0, v3, vcc
	global_load_dword v31, v[32:33], off offset:2048
.LBB0_862:
	s_or_b64 exec, exec, s[6:7]
	v_add_u32_e32 v32, 0x640, v38
	v_cmp_ge_i32_e32 vcc, s3, v32
	s_and_saveexec_b64 s[6:7], vcc
	s_cbranch_execz .LBB0_864
	v_add_co_u32_e32 v32, vcc, 0x1000, v2
	s_nop 1
	v_addc_co_u32_e32 v33, vcc, 0, v3, vcc
	global_load_dword v29, v[32:33], off offset:2304
.LBB0_864:
	s_or_b64 exec, exec, s[6:7]
	v_add_u32_e32 v32, 0x680, v38
	v_cmp_ge_i32_e32 vcc, s3, v32
	v_mov_b32_e32 v32, 0
	v_mov_b32_e32 v33, 0
	s_and_saveexec_b64 s[6:7], vcc
	s_cbranch_execz .LBB0_866
	v_add_co_u32_e32 v34, vcc, 0x1000, v2
	s_nop 1
	v_addc_co_u32_e32 v35, vcc, 0, v3, vcc
	global_load_dword v33, v[34:35], off offset:2560
.LBB0_866:
	s_or_b64 exec, exec, s[6:7]
	v_add_u32_e32 v34, 0x6c0, v38
	v_cmp_ge_i32_e32 vcc, s3, v34
	s_and_saveexec_b64 s[6:7], vcc
	s_cbranch_execz .LBB0_868
	v_add_co_u32_e32 v34, vcc, 0x1000, v2
	s_nop 1
	v_addc_co_u32_e32 v35, vcc, 0, v3, vcc
	global_load_dword v32, v[34:35], off offset:2816
.LBB0_868:
	s_or_b64 exec, exec, s[6:7]
	v_add_u32_e32 v34, 0x700, v38
	v_cmp_ge_i32_e32 vcc, s3, v34
	v_mov_b32_e32 v34, 0
	v_mov_b32_e32 v35, 0
	s_and_saveexec_b64 s[6:7], vcc
	s_cbranch_execz .LBB0_870
	v_add_co_u32_e32 v36, vcc, 0x1000, v2
	s_nop 1
	v_addc_co_u32_e32 v37, vcc, 0, v3, vcc
	global_load_dword v35, v[36:37], off offset:3072
.LBB0_870:
	s_or_b64 exec, exec, s[6:7]
	v_add_u32_e32 v36, 0x740, v38
	v_cmp_ge_i32_e32 vcc, s3, v36
	s_and_saveexec_b64 s[6:7], vcc
	s_cbranch_execz .LBB0_872
	v_add_co_u32_e32 v36, vcc, 0x1000, v2
	s_nop 1
	v_addc_co_u32_e32 v37, vcc, 0, v3, vcc
	global_load_dword v34, v[36:37], off offset:3328
.LBB0_872:
	s_or_b64 exec, exec, s[6:7]
	v_add_u32_e32 v36, 0x780, v38
	v_cmp_ge_i32_e32 vcc, s3, v36
	v_mov_b32_e32 v36, 0
	v_mov_b32_e32 v37, 0
	s_and_saveexec_b64 s[6:7], vcc
	s_cbranch_execz .LBB0_874
	v_add_co_u32_e32 v40, vcc, 0x1000, v2
	s_nop 1
	v_addc_co_u32_e32 v41, vcc, 0, v3, vcc
	global_load_dword v37, v[40:41], off offset:3584
.LBB0_874:
	s_or_b64 exec, exec, s[6:7]
	v_add_u32_e32 v38, 0x7c0, v38
	v_cmp_ge_i32_e32 vcc, s3, v38
	s_and_saveexec_b64 s[6:7], vcc
	s_cbranch_execz .LBB0_876
	v_add_co_u32_e32 v38, vcc, 0x1000, v2
	s_nop 1
	v_addc_co_u32_e32 v39, vcc, 0, v3, vcc
	global_load_dword v36, v[38:39], off offset:3840

.LBB0_877:
	s_cmpk_lt_u32 s3, 0xbff
	s_mov_b64 s[6:7], -1
	s_cbranch_scc1 .LBB0_879
	v_add_co_u32_e32 v54, vcc, 0x2000, v2
	s_mov_b64 s[6:7], 0
	s_nop 0
	v_addc_co_u32_e32 v55, vcc, 0, v3, vcc
	global_load_dword v39, v[54:55], off
	global_load_dword v38, v[54:55], off offset:256
	global_load_dword v41, v[54:55], off offset:512
	global_load_dword v40, v[54:55], off offset:768
	global_load_dword v43, v[54:55], off offset:1024
	global_load_dword v42, v[54:55], off offset:1280
	global_load_dword v45, v[54:55], off offset:1536
	global_load_dword v44, v[54:55], off offset:1792
	global_load_dword v47, v[54:55], off offset:2048
	global_load_dword v46, v[54:55], off offset:2304
	global_load_dword v49, v[54:55], off offset:2560
	global_load_dword v48, v[54:55], off offset:2816
	global_load_dword v51, v[54:55], off offset:3072
	global_load_dword v50, v[54:55], off offset:3328
	global_load_dword v53, v[54:55], off offset:3584
	global_load_dword v52, v[54:55], off offset:3840
.LBB0_879:
	s_andn2_b64 vcc, exec, s[6:7]
	s_cbranch_vccnz .LBB0_914
	v_mov_b32_e32 v39, 0
	s_cmpk_lt_u32 s3, 0x800
	v_mov_b32_e32 v38, 0
	v_mov_b32_e32 v41, 0
	v_mov_b32_e32 v40, 0
	v_mov_b32_e32 v43, 0
	v_mov_b32_e32 v42, 0
	v_mov_b32_e32 v45, 0
	v_mov_b32_e32 v44, 0
	v_mov_b32_e32 v47, 0
	v_mov_b32_e32 v46, 0
	v_mov_b32_e32 v49, 0
	v_mov_b32_e32 v48, 0
	v_mov_b32_e32 v51, 0
	v_mov_b32_e32 v50, 0
	v_mov_b32_e32 v53, 0
	v_mov_b32_e32 v52, 0
	s_cbranch_scc1 .LBB0_914
	v_mov_b32_e32 v54, v30
	v_mov_b32_e32 v39, 0
	v_add_u32_e32 v38, 0x800, v54
	v_cmp_ge_i32_e32 vcc, s3, v38
	v_mov_b32_e32 v38, 0
	s_and_saveexec_b64 s[6:7], vcc
	s_cbranch_execz .LBB0_883
	v_add_co_u32_e32 v40, vcc, 0x2000, v2
	s_nop 1
	v_addc_co_u32_e32 v41, vcc, 0, v3, vcc
	global_load_dword v39, v[40:41], off
.LBB0_883:
	s_or_b64 exec, exec, s[6:7]
	v_add_u32_e32 v40, 0x840, v54
	v_cmp_ge_i32_e32 vcc, s3, v40
	s_and_saveexec_b64 s[6:7], vcc
	s_cbranch_execz .LBB0_885
	v_add_co_u32_e32 v40, vcc, 0x2000, v2
	s_nop 1
	v_addc_co_u32_e32 v41, vcc, 0, v3, vcc
	global_load_dword v38, v[40:41], off offset:256
.LBB0_885:
	s_or_b64 exec, exec, s[6:7]
	v_add_u32_e32 v40, 0x880, v54
	v_cmp_ge_i32_e32 vcc, s3, v40
	v_mov_b32_e32 v40, 0
	v_mov_b32_e32 v41, 0
	s_and_saveexec_b64 s[6:7], vcc
	s_cbranch_execz .LBB0_887
	v_add_co_u32_e32 v42, vcc, 0x2000, v2
	s_nop 1
	v_addc_co_u32_e32 v43, vcc, 0, v3, vcc
	global_load_dword v41, v[42:43], off offset:512
.LBB0_887:
	s_or_b64 exec, exec, s[6:7]
	v_add_u32_e32 v42, 0x8c0, v54
	v_cmp_ge_i32_e32 vcc, s3, v42
	s_and_saveexec_b64 s[6:7], vcc
	s_cbranch_execz .LBB0_889
	v_add_co_u32_e32 v42, vcc, 0x2000, v2
	s_nop 1
	v_addc_co_u32_e32 v43, vcc, 0, v3, vcc
	global_load_dword v40, v[42:43], off offset:768
.LBB0_889:
	s_or_b64 exec, exec, s[6:7]
	v_add_u32_e32 v42, 0x900, v54
	v_cmp_ge_i32_e32 vcc, s3, v42
	v_mov_b32_e32 v42, 0
	v_mov_b32_e32 v43, 0
	s_and_saveexec_b64 s[6:7], vcc
	s_cbranch_execz .LBB0_891
	v_add_co_u32_e32 v44, vcc, 0x2000, v2
	s_nop 1
	v_addc_co_u32_e32 v45, vcc, 0, v3, vcc
	global_load_dword v43, v[44:45], off offset:1024
.LBB0_891:
	s_or_b64 exec, exec, s[6:7]
	v_add_u32_e32 v44, 0x940, v54
	v_cmp_ge_i32_e32 vcc, s3, v44
	s_and_saveexec_b64 s[6:7], vcc
	s_cbranch_execz .LBB0_893
	v_add_co_u32_e32 v44, vcc, 0x2000, v2
	s_nop 1
	v_addc_co_u32_e32 v45, vcc, 0, v3, vcc
	global_load_dword v42, v[44:45], off offset:1280
.LBB0_893:
	s_or_b64 exec, exec, s[6:7]
	v_add_u32_e32 v44, 0x980, v54
	v_cmp_ge_i32_e32 vcc, s3, v44
	v_mov_b32_e32 v44, 0
	v_mov_b32_e32 v45, 0
	s_and_saveexec_b64 s[6:7], vcc
	s_cbranch_execz .LBB0_895
	v_add_co_u32_e32 v46, vcc, 0x2000, v2
	s_nop 1
	v_addc_co_u32_e32 v47, vcc, 0, v3, vcc
	global_load_dword v45, v[46:47], off offset:1536
.LBB0_895:
	s_or_b64 exec, exec, s[6:7]
	v_add_u32_e32 v46, 0x9c0, v54
	v_cmp_ge_i32_e32 vcc, s3, v46
	s_and_saveexec_b64 s[6:7], vcc
	s_cbranch_execz .LBB0_897
	v_add_co_u32_e32 v46, vcc, 0x2000, v2
	s_nop 1
	v_addc_co_u32_e32 v47, vcc, 0, v3, vcc
	global_load_dword v44, v[46:47], off offset:1792
.LBB0_897:
	s_or_b64 exec, exec, s[6:7]
	v_add_u32_e32 v46, 0xa00, v54
	v_cmp_ge_i32_e32 vcc, s3, v46
	v_mov_b32_e32 v46, 0
	v_mov_b32_e32 v47, 0
	s_and_saveexec_b64 s[6:7], vcc
	s_cbranch_execz .LBB0_899
	v_add_co_u32_e32 v48, vcc, 0x2000, v2
	s_nop 1
	v_addc_co_u32_e32 v49, vcc, 0, v3, vcc
	global_load_dword v47, v[48:49], off offset:2048
.LBB0_899:
	s_or_b64 exec, exec, s[6:7]
	v_add_u32_e32 v48, 0xa40, v54
	v_cmp_ge_i32_e32 vcc, s3, v48
	s_and_saveexec_b64 s[6:7], vcc
	s_cbranch_execz .LBB0_901
	v_add_co_u32_e32 v48, vcc, 0x2000, v2
	s_nop 1
	v_addc_co_u32_e32 v49, vcc, 0, v3, vcc
	global_load_dword v46, v[48:49], off offset:2304
.LBB0_901:
	s_or_b64 exec, exec, s[6:7]
	v_add_u32_e32 v48, 0xa80, v54
	v_cmp_ge_i32_e32 vcc, s3, v48
	v_mov_b32_e32 v48, 0
	v_mov_b32_e32 v49, 0
	s_and_saveexec_b64 s[6:7], vcc
	s_cbranch_execz .LBB0_903
	v_add_co_u32_e32 v50, vcc, 0x2000, v2
	s_nop 1
	v_addc_co_u32_e32 v51, vcc, 0, v3, vcc
	global_load_dword v49, v[50:51], off offset:2560
.LBB0_903:
	s_or_b64 exec, exec, s[6:7]
	v_add_u32_e32 v50, 0xac0, v54
	v_cmp_ge_i32_e32 vcc, s3, v50
	s_and_saveexec_b64 s[6:7], vcc
	s_cbranch_execz .LBB0_905
	v_add_co_u32_e32 v50, vcc, 0x2000, v2
	s_nop 1
	v_addc_co_u32_e32 v51, vcc, 0, v3, vcc
	global_load_dword v48, v[50:51], off offset:2816
.LBB0_905:
	s_or_b64 exec, exec, s[6:7]
	v_add_u32_e32 v50, 0xb00, v54
	v_cmp_ge_i32_e32 vcc, s3, v50
	v_mov_b32_e32 v50, 0
	v_mov_b32_e32 v51, 0
	s_and_saveexec_b64 s[6:7], vcc
	s_cbranch_execz .LBB0_907
	v_add_co_u32_e32 v52, vcc, 0x2000, v2
	s_nop 1
	v_addc_co_u32_e32 v53, vcc, 0, v3, vcc
	global_load_dword v51, v[52:53], off offset:3072
.LBB0_907:
	s_or_b64 exec, exec, s[6:7]
	v_add_u32_e32 v52, 0xb40, v54
	v_cmp_ge_i32_e32 vcc, s3, v52
	s_and_saveexec_b64 s[6:7], vcc
	s_cbranch_execz .LBB0_909
	v_add_co_u32_e32 v52, vcc, 0x2000, v2
	s_nop 1
	v_addc_co_u32_e32 v53, vcc, 0, v3, vcc
	global_load_dword v50, v[52:53], off offset:3328
.LBB0_909:
	s_or_b64 exec, exec, s[6:7]
	v_add_u32_e32 v52, 0xb80, v54
	v_cmp_ge_i32_e32 vcc, s3, v52
	v_mov_b32_e32 v52, 0
	v_mov_b32_e32 v53, 0
	s_and_saveexec_b64 s[6:7], vcc
	s_cbranch_execz .LBB0_911
	v_add_co_u32_e32 v56, vcc, 0x2000, v2
	s_nop 1
	v_addc_co_u32_e32 v57, vcc, 0, v3, vcc
	global_load_dword v53, v[56:57], off offset:3584
.LBB0_911:
	s_or_b64 exec, exec, s[6:7]
	v_add_u32_e32 v54, 0xbc0, v54
	v_cmp_ge_i32_e32 vcc, s3, v54
	s_and_saveexec_b64 s[6:7], vcc
	s_cbranch_execz .LBB0_913
	v_add_co_u32_e32 v54, vcc, 0x2000, v2
	s_nop 1
	v_addc_co_u32_e32 v55, vcc, 0, v3, vcc
	global_load_dword v52, v[54:55], off offset:3840

.LBB0_914:
	s_cmpk_lt_u32 s3, 0xfff
	s_mov_b64 s[6:7], -1
	s_cbranch_scc1 .LBB0_916
	v_add_co_u32_e32 v70, vcc, 0x3000, v2
	s_mov_b64 s[6:7], 0
	v_addc_co_u32_e32 v71, vcc, 0, v3, vcc
	global_load_dword v55, v[70:71], off
	global_load_dword v54, v[70:71], off offset:256
	global_load_dword v57, v[70:71], off offset:512
	global_load_dword v56, v[70:71], off offset:768
	global_load_dword v59, v[70:71], off offset:1024
	global_load_dword v58, v[70:71], off offset:1280
	global_load_dword v61, v[70:71], off offset:1536
	global_load_dword v60, v[70:71], off offset:1792
	global_load_dword v63, v[70:71], off offset:2048
	global_load_dword v62, v[70:71], off offset:2304
	global_load_dword v65, v[70:71], off offset:2560
	global_load_dword v64, v[70:71], off offset:2816
	global_load_dword v67, v[70:71], off offset:3072
	global_load_dword v66, v[70:71], off offset:3328
	global_load_dword v69, v[70:71], off offset:3584
	global_load_dword v68, v[70:71], off offset:3840
.LBB0_916:
	s_andn2_b64 vcc, exec, s[6:7]
	s_cbranch_vccnz .LBB0_951
	v_mov_b32_e32 v55, 0
	s_cmpk_lt_u32 s3, 0xc00
	v_mov_b32_e32 v54, 0
	v_mov_b32_e32 v57, 0
	v_mov_b32_e32 v56, 0
	v_mov_b32_e32 v59, 0
	v_mov_b32_e32 v58, 0
	v_mov_b32_e32 v61, 0
	v_mov_b32_e32 v60, 0
	v_mov_b32_e32 v63, 0
	v_mov_b32_e32 v62, 0
	v_mov_b32_e32 v65, 0
	v_mov_b32_e32 v64, 0
	v_mov_b32_e32 v67, 0
	v_mov_b32_e32 v66, 0
	v_mov_b32_e32 v69, 0
	v_mov_b32_e32 v68, 0
	s_cbranch_scc1 .LBB0_951
	v_mov_b32_e32 v70, v30
	v_mov_b32_e32 v55, 0
	v_add_u32_e32 v54, 0xc00, v70
	v_cmp_ge_i32_e32 vcc, s3, v54
	v_mov_b32_e32 v54, 0
	s_and_saveexec_b64 s[6:7], vcc
	s_cbranch_execz .LBB0_920
	v_add_co_u32_e32 v56, vcc, 0x3000, v2
	s_nop 1
	v_addc_co_u32_e32 v57, vcc, 0, v3, vcc
	global_load_dword v55, v[56:57], off
.LBB0_920:
	s_or_b64 exec, exec, s[6:7]
	v_add_u32_e32 v56, 0xc40, v70
	v_cmp_ge_i32_e32 vcc, s3, v56
	s_and_saveexec_b64 s[6:7], vcc
	s_cbranch_execz .LBB0_922
	v_add_co_u32_e32 v56, vcc, 0x3000, v2
	s_nop 1
	v_addc_co_u32_e32 v57, vcc, 0, v3, vcc
	global_load_dword v54, v[56:57], off offset:256
.LBB0_922:
	s_or_b64 exec, exec, s[6:7]
	v_add_u32_e32 v56, 0xc80, v70
	v_cmp_ge_i32_e32 vcc, s3, v56
	v_mov_b32_e32 v56, 0
	v_mov_b32_e32 v57, 0
	s_and_saveexec_b64 s[6:7], vcc
	s_cbranch_execz .LBB0_924
	v_add_co_u32_e32 v58, vcc, 0x3000, v2
	s_nop 1
	v_addc_co_u32_e32 v59, vcc, 0, v3, vcc
	global_load_dword v57, v[58:59], off offset:512
.LBB0_924:
	s_or_b64 exec, exec, s[6:7]
	v_add_u32_e32 v58, 0xcc0, v70
	v_cmp_ge_i32_e32 vcc, s3, v58
	s_and_saveexec_b64 s[6:7], vcc
	s_cbranch_execz .LBB0_926
	v_add_co_u32_e32 v58, vcc, 0x3000, v2
	s_nop 1
	v_addc_co_u32_e32 v59, vcc, 0, v3, vcc
	global_load_dword v56, v[58:59], off offset:768
.LBB0_926:
	s_or_b64 exec, exec, s[6:7]
	v_add_u32_e32 v58, 0xd00, v70
	v_cmp_ge_i32_e32 vcc, s3, v58
	v_mov_b32_e32 v58, 0
	v_mov_b32_e32 v59, 0
	s_and_saveexec_b64 s[6:7], vcc
	s_cbranch_execz .LBB0_928
	v_add_co_u32_e32 v60, vcc, 0x3000, v2
	s_nop 1
	v_addc_co_u32_e32 v61, vcc, 0, v3, vcc
	global_load_dword v59, v[60:61], off offset:1024
.LBB0_928:
	s_or_b64 exec, exec, s[6:7]
	v_add_u32_e32 v60, 0xd40, v70
	v_cmp_ge_i32_e32 vcc, s3, v60
	s_and_saveexec_b64 s[6:7], vcc
	s_cbranch_execz .LBB0_930
	v_add_co_u32_e32 v60, vcc, 0x3000, v2
	s_nop 1
	v_addc_co_u32_e32 v61, vcc, 0, v3, vcc
	global_load_dword v58, v[60:61], off offset:1280
.LBB0_930:
	s_or_b64 exec, exec, s[6:7]
	v_add_u32_e32 v60, 0xd80, v70
	v_cmp_ge_i32_e32 vcc, s3, v60
	v_mov_b32_e32 v60, 0
	v_mov_b32_e32 v61, 0
	s_and_saveexec_b64 s[6:7], vcc
	s_cbranch_execz .LBB0_932
	v_add_co_u32_e32 v62, vcc, 0x3000, v2
	s_nop 1
	v_addc_co_u32_e32 v63, vcc, 0, v3, vcc
	global_load_dword v61, v[62:63], off offset:1536
.LBB0_932:
	s_or_b64 exec, exec, s[6:7]
	v_add_u32_e32 v62, 0xdc0, v70
	v_cmp_ge_i32_e32 vcc, s3, v62
	s_and_saveexec_b64 s[6:7], vcc
	s_cbranch_execz .LBB0_934
	v_add_co_u32_e32 v62, vcc, 0x3000, v2
	s_nop 1
	v_addc_co_u32_e32 v63, vcc, 0, v3, vcc
	global_load_dword v60, v[62:63], off offset:1792
.LBB0_934:
	s_or_b64 exec, exec, s[6:7]
	v_add_u32_e32 v62, 0xe00, v70
	v_cmp_ge_i32_e32 vcc, s3, v62
	v_mov_b32_e32 v62, 0
	v_mov_b32_e32 v63, 0
	s_and_saveexec_b64 s[6:7], vcc
	s_cbranch_execz .LBB0_936
	v_add_co_u32_e32 v64, vcc, 0x3000, v2
	s_nop 1
	v_addc_co_u32_e32 v65, vcc, 0, v3, vcc
	global_load_dword v63, v[64:65], off offset:2048
.LBB0_936:
	s_or_b64 exec, exec, s[6:7]
	v_add_u32_e32 v64, 0xe40, v70
	v_cmp_ge_i32_e32 vcc, s3, v64
	s_and_saveexec_b64 s[6:7], vcc
	s_cbranch_execz .LBB0_938
	v_add_co_u32_e32 v64, vcc, 0x3000, v2
	s_nop 1
	v_addc_co_u32_e32 v65, vcc, 0, v3, vcc
	global_load_dword v62, v[64:65], off offset:2304
.LBB0_938:
	s_or_b64 exec, exec, s[6:7]
	v_add_u32_e32 v64, 0xe80, v70
	v_cmp_ge_i32_e32 vcc, s3, v64
	v_mov_b32_e32 v64, 0
	v_mov_b32_e32 v65, 0
	s_and_saveexec_b64 s[6:7], vcc
	s_cbranch_execz .LBB0_940
	v_add_co_u32_e32 v66, vcc, 0x3000, v2
	s_nop 1
	v_addc_co_u32_e32 v67, vcc, 0, v3, vcc
	global_load_dword v65, v[66:67], off offset:2560
.LBB0_940:
	s_or_b64 exec, exec, s[6:7]
	v_add_u32_e32 v66, 0xec0, v70
	v_cmp_ge_i32_e32 vcc, s3, v66
	s_and_saveexec_b64 s[6:7], vcc
	s_cbranch_execz .LBB0_942
	v_add_co_u32_e32 v66, vcc, 0x3000, v2
	s_nop 1
	v_addc_co_u32_e32 v67, vcc, 0, v3, vcc
	global_load_dword v64, v[66:67], off offset:2816
.LBB0_942:
	s_or_b64 exec, exec, s[6:7]
	v_add_u32_e32 v66, 0xf00, v70
	v_cmp_ge_i32_e32 vcc, s3, v66
	v_mov_b32_e32 v66, 0
	v_mov_b32_e32 v67, 0
	s_and_saveexec_b64 s[6:7], vcc
	s_cbranch_execz .LBB0_944
	v_add_co_u32_e32 v68, vcc, 0x3000, v2
	s_nop 1
	v_addc_co_u32_e32 v69, vcc, 0, v3, vcc
	global_load_dword v67, v[68:69], off offset:3072
.LBB0_944:
	s_or_b64 exec, exec, s[6:7]
	v_add_u32_e32 v68, 0xf40, v70
	v_cmp_ge_i32_e32 vcc, s3, v68
	s_and_saveexec_b64 s[6:7], vcc
	s_cbranch_execz .LBB0_946
	v_add_co_u32_e32 v68, vcc, 0x3000, v2
	s_nop 1
	v_addc_co_u32_e32 v69, vcc, 0, v3, vcc
	global_load_dword v66, v[68:69], off offset:3328
.LBB0_946:
	s_or_b64 exec, exec, s[6:7]
	v_add_u32_e32 v68, 0xf80, v70
	v_cmp_ge_i32_e32 vcc, s3, v68
	v_mov_b32_e32 v68, 0
	v_mov_b32_e32 v69, 0
	s_and_saveexec_b64 s[6:7], vcc
	s_cbranch_execz .LBB0_948
	v_add_co_u32_e32 v72, vcc, 0x3000, v2
	s_nop 1
	v_addc_co_u32_e32 v73, vcc, 0, v3, vcc
	global_load_dword v69, v[72:73], off offset:3584
.LBB0_948:
	s_or_b64 exec, exec, s[6:7]
	v_add_u32_e32 v70, 0xfc0, v70
	v_cmp_ge_i32_e32 vcc, s3, v70
	s_and_saveexec_b64 s[6:7], vcc
	s_cbranch_execz .LBB0_950
	v_add_co_u32_e32 v70, vcc, 0x3000, v2
	s_nop 1
	v_addc_co_u32_e32 v71, vcc, 0, v3, vcc
	global_load_dword v68, v[70:71], off offset:3840

.LBB0_951:
	s_cmpk_lt_u32 s3, 0x13ff
	s_mov_b64 s[6:7], -1
	s_cbranch_scc1 .LBB0_953
	v_add_co_u32_e32 v86, vcc, 0x4000, v2
	s_mov_b64 s[6:7], 0
	s_nop 0
	v_addc_co_u32_e32 v87, vcc, 0, v3, vcc
	global_load_dword v71, v[86:87], off
	global_load_dword v70, v[86:87], off offset:256
	global_load_dword v73, v[86:87], off offset:512
	global_load_dword v72, v[86:87], off offset:768
	global_load_dword v75, v[86:87], off offset:1024
	global_load_dword v74, v[86:87], off offset:1280
	global_load_dword v77, v[86:87], off offset:1536
	global_load_dword v76, v[86:87], off offset:1792
	global_load_dword v79, v[86:87], off offset:2048
	global_load_dword v78, v[86:87], off offset:2304
	global_load_dword v81, v[86:87], off offset:2560
	global_load_dword v80, v[86:87], off offset:2816
	global_load_dword v83, v[86:87], off offset:3072
	global_load_dword v82, v[86:87], off offset:3328
	global_load_dword v85, v[86:87], off offset:3584
	global_load_dword v84, v[86:87], off offset:3840
.LBB0_953:
	s_andn2_b64 vcc, exec, s[6:7]
	s_cbranch_vccnz .LBB0_988
	v_mov_b32_e32 v71, 0
	s_cmpk_lt_u32 s3, 0x1000
	v_mov_b32_e32 v70, 0
	v_mov_b32_e32 v73, 0
	v_mov_b32_e32 v72, 0
	v_mov_b32_e32 v75, 0
	v_mov_b32_e32 v74, 0
	v_mov_b32_e32 v77, 0
	v_mov_b32_e32 v76, 0
	v_mov_b32_e32 v79, 0
	v_mov_b32_e32 v78, 0
	v_mov_b32_e32 v81, 0
	v_mov_b32_e32 v80, 0
	v_mov_b32_e32 v83, 0
	v_mov_b32_e32 v82, 0
	v_mov_b32_e32 v85, 0
	v_mov_b32_e32 v84, 0
	s_cbranch_scc1 .LBB0_988
	v_mov_b32_e32 v86, v30
	v_mov_b32_e32 v71, 0
	v_add_u32_e32 v70, 0x1000, v86
	v_cmp_ge_i32_e32 vcc, s3, v70
	v_mov_b32_e32 v70, 0
	s_and_saveexec_b64 s[6:7], vcc
	s_cbranch_execz .LBB0_957
	v_add_co_u32_e32 v72, vcc, 0x4000, v2
	s_nop 1
	v_addc_co_u32_e32 v73, vcc, 0, v3, vcc
	global_load_dword v71, v[72:73], off
.LBB0_957:
	s_or_b64 exec, exec, s[6:7]
	v_add_u32_e32 v72, 0x1040, v86
	v_cmp_ge_i32_e32 vcc, s3, v72
	s_and_saveexec_b64 s[6:7], vcc
	s_cbranch_execz .LBB0_959
	v_add_co_u32_e32 v72, vcc, 0x4000, v2
	s_nop 1
	v_addc_co_u32_e32 v73, vcc, 0, v3, vcc
	global_load_dword v70, v[72:73], off offset:256
.LBB0_959:
	s_or_b64 exec, exec, s[6:7]
	v_add_u32_e32 v72, 0x1080, v86
	v_cmp_ge_i32_e32 vcc, s3, v72
	v_mov_b32_e32 v72, 0
	v_mov_b32_e32 v73, 0
	s_and_saveexec_b64 s[6:7], vcc
	s_cbranch_execz .LBB0_961
	v_add_co_u32_e32 v74, vcc, 0x4000, v2
	s_nop 1
	v_addc_co_u32_e32 v75, vcc, 0, v3, vcc
	global_load_dword v73, v[74:75], off offset:512
.LBB0_961:
	s_or_b64 exec, exec, s[6:7]
	v_add_u32_e32 v74, 0x10c0, v86
	v_cmp_ge_i32_e32 vcc, s3, v74
	s_and_saveexec_b64 s[6:7], vcc
	s_cbranch_execz .LBB0_963
	v_add_co_u32_e32 v74, vcc, 0x4000, v2
	s_nop 1
	v_addc_co_u32_e32 v75, vcc, 0, v3, vcc
	global_load_dword v72, v[74:75], off offset:768
.LBB0_963:
	s_or_b64 exec, exec, s[6:7]
	v_add_u32_e32 v74, 0x1100, v86
	v_cmp_ge_i32_e32 vcc, s3, v74
	v_mov_b32_e32 v74, 0
	v_mov_b32_e32 v75, 0
	s_and_saveexec_b64 s[6:7], vcc
	s_cbranch_execz .LBB0_965
	v_add_co_u32_e32 v76, vcc, 0x4000, v2
	s_nop 1
	v_addc_co_u32_e32 v77, vcc, 0, v3, vcc
	global_load_dword v75, v[76:77], off offset:1024
.LBB0_965:
	s_or_b64 exec, exec, s[6:7]
	v_add_u32_e32 v76, 0x1140, v86
	v_cmp_ge_i32_e32 vcc, s3, v76
	s_and_saveexec_b64 s[6:7], vcc
	s_cbranch_execz .LBB0_967
	v_add_co_u32_e32 v76, vcc, 0x4000, v2
	s_nop 1
	v_addc_co_u32_e32 v77, vcc, 0, v3, vcc
	global_load_dword v74, v[76:77], off offset:1280
.LBB0_967:
	s_or_b64 exec, exec, s[6:7]
	v_add_u32_e32 v76, 0x1180, v86
	v_cmp_ge_i32_e32 vcc, s3, v76
	v_mov_b32_e32 v76, 0
	v_mov_b32_e32 v77, 0
	s_and_saveexec_b64 s[6:7], vcc
	s_cbranch_execz .LBB0_969
	v_add_co_u32_e32 v78, vcc, 0x4000, v2
	s_nop 1
	v_addc_co_u32_e32 v79, vcc, 0, v3, vcc
	global_load_dword v77, v[78:79], off offset:1536
.LBB0_969:
	s_or_b64 exec, exec, s[6:7]
	v_add_u32_e32 v78, 0x11c0, v86
	v_cmp_ge_i32_e32 vcc, s3, v78
	s_and_saveexec_b64 s[6:7], vcc
	s_cbranch_execz .LBB0_971
	v_add_co_u32_e32 v78, vcc, 0x4000, v2
	s_nop 1
	v_addc_co_u32_e32 v79, vcc, 0, v3, vcc
	global_load_dword v76, v[78:79], off offset:1792
.LBB0_971:
	s_or_b64 exec, exec, s[6:7]
	v_add_u32_e32 v78, 0x1200, v86
	v_cmp_ge_i32_e32 vcc, s3, v78
	v_mov_b32_e32 v78, 0
	v_mov_b32_e32 v79, 0
	s_and_saveexec_b64 s[6:7], vcc
	s_cbranch_execz .LBB0_973
	v_add_co_u32_e32 v80, vcc, 0x4000, v2
	s_nop 1
	v_addc_co_u32_e32 v81, vcc, 0, v3, vcc
	global_load_dword v79, v[80:81], off offset:2048
.LBB0_973:
	s_or_b64 exec, exec, s[6:7]
	v_add_u32_e32 v80, 0x1240, v86
	v_cmp_ge_i32_e32 vcc, s3, v80
	s_and_saveexec_b64 s[6:7], vcc
	s_cbranch_execz .LBB0_975
	v_add_co_u32_e32 v80, vcc, 0x4000, v2
	s_nop 1
	v_addc_co_u32_e32 v81, vcc, 0, v3, vcc
	global_load_dword v78, v[80:81], off offset:2304
.LBB0_975:
	s_or_b64 exec, exec, s[6:7]
	v_add_u32_e32 v80, 0x1280, v86
	v_cmp_ge_i32_e32 vcc, s3, v80
	v_mov_b32_e32 v80, 0
	v_mov_b32_e32 v81, 0
	s_and_saveexec_b64 s[6:7], vcc
	s_cbranch_execz .LBB0_977
	v_add_co_u32_e32 v82, vcc, 0x4000, v2
	s_nop 1
	v_addc_co_u32_e32 v83, vcc, 0, v3, vcc
	global_load_dword v81, v[82:83], off offset:2560
.LBB0_977:
	s_or_b64 exec, exec, s[6:7]
	v_add_u32_e32 v82, 0x12c0, v86
	v_cmp_ge_i32_e32 vcc, s3, v82
	s_and_saveexec_b64 s[6:7], vcc
	s_cbranch_execz .LBB0_979
	v_add_co_u32_e32 v82, vcc, 0x4000, v2
	s_nop 1
	v_addc_co_u32_e32 v83, vcc, 0, v3, vcc
	global_load_dword v80, v[82:83], off offset:2816
.LBB0_979:
	s_or_b64 exec, exec, s[6:7]
	v_add_u32_e32 v82, 0x1300, v86
	v_cmp_ge_i32_e32 vcc, s3, v82
	v_mov_b32_e32 v82, 0
	v_mov_b32_e32 v83, 0
	s_and_saveexec_b64 s[6:7], vcc
	s_cbranch_execz .LBB0_981
	v_add_co_u32_e32 v84, vcc, 0x4000, v2
	s_nop 1
	v_addc_co_u32_e32 v85, vcc, 0, v3, vcc
	global_load_dword v83, v[84:85], off offset:3072
.LBB0_981:
	s_or_b64 exec, exec, s[6:7]
	v_add_u32_e32 v84, 0x1340, v86
	v_cmp_ge_i32_e32 vcc, s3, v84
	s_and_saveexec_b64 s[6:7], vcc
	s_cbranch_execz .LBB0_983
	v_add_co_u32_e32 v84, vcc, 0x4000, v2
	s_nop 1
	v_addc_co_u32_e32 v85, vcc, 0, v3, vcc
	global_load_dword v82, v[84:85], off offset:3328
.LBB0_983:
	s_or_b64 exec, exec, s[6:7]
	v_add_u32_e32 v84, 0x1380, v86
	v_cmp_ge_i32_e32 vcc, s3, v84
	v_mov_b32_e32 v84, 0
	v_mov_b32_e32 v85, 0
	s_and_saveexec_b64 s[6:7], vcc
	s_cbranch_execz .LBB0_985
	v_add_co_u32_e32 v88, vcc, 0x4000, v2
	s_nop 1
	v_addc_co_u32_e32 v89, vcc, 0, v3, vcc
	global_load_dword v85, v[88:89], off offset:3584
.LBB0_985:
	s_or_b64 exec, exec, s[6:7]
	v_add_u32_e32 v86, 0x13c0, v86
	v_cmp_ge_i32_e32 vcc, s3, v86
	s_and_saveexec_b64 s[6:7], vcc
	s_cbranch_execz .LBB0_987
	v_add_co_u32_e32 v86, vcc, 0x4000, v2
	s_nop 1
	v_addc_co_u32_e32 v87, vcc, 0, v3, vcc
	global_load_dword v84, v[86:87], off offset:3840

.LBB0_988:
	s_cmpk_lt_u32 s3, 0x17ff
	s_mov_b64 s[6:7], -1
	s_cbranch_scc1 .LBB0_990
	v_add_co_u32_e32 v102, vcc, 0x5000, v2
	s_mov_b64 s[6:7], 0
	s_nop 0
	v_addc_co_u32_e32 v103, vcc, 0, v3, vcc
	global_load_dword v87, v[102:103], off
	global_load_dword v86, v[102:103], off offset:256
	global_load_dword v89, v[102:103], off offset:512
	global_load_dword v88, v[102:103], off offset:768
	global_load_dword v91, v[102:103], off offset:1024
	global_load_dword v90, v[102:103], off offset:1280
	global_load_dword v93, v[102:103], off offset:1536
	global_load_dword v92, v[102:103], off offset:1792
	global_load_dword v95, v[102:103], off offset:2048
	global_load_dword v94, v[102:103], off offset:2304
	global_load_dword v97, v[102:103], off offset:2560
	global_load_dword v96, v[102:103], off offset:2816
	global_load_dword v99, v[102:103], off offset:3072
	global_load_dword v98, v[102:103], off offset:3328
	global_load_dword v101, v[102:103], off offset:3584
	global_load_dword v100, v[102:103], off offset:3840
.LBB0_990:
	s_andn2_b64 vcc, exec, s[6:7]
	s_cbranch_vccnz .LBB0_1025
	v_mov_b32_e32 v87, 0
	s_cmpk_lt_u32 s3, 0x1400
	v_mov_b32_e32 v86, 0
	v_mov_b32_e32 v89, 0
	v_mov_b32_e32 v88, 0
	v_mov_b32_e32 v91, 0
	v_mov_b32_e32 v90, 0
	v_mov_b32_e32 v93, 0
	v_mov_b32_e32 v92, 0
	v_mov_b32_e32 v95, 0
	v_mov_b32_e32 v94, 0
	v_mov_b32_e32 v97, 0
	v_mov_b32_e32 v96, 0
	v_mov_b32_e32 v99, 0
	v_mov_b32_e32 v98, 0
	v_mov_b32_e32 v101, 0
	v_mov_b32_e32 v100, 0
	s_cbranch_scc1 .LBB0_1025
	v_mov_b32_e32 v102, v30
	v_mov_b32_e32 v87, 0
	v_add_u32_e32 v86, 0x1400, v102
	v_cmp_ge_i32_e32 vcc, s3, v86
	v_mov_b32_e32 v86, 0
	s_and_saveexec_b64 s[6:7], vcc
	s_cbranch_execz .LBB0_994
	v_add_co_u32_e32 v88, vcc, 0x5000, v2
	s_nop 1
	v_addc_co_u32_e32 v89, vcc, 0, v3, vcc
	global_load_dword v87, v[88:89], off
.LBB0_994:
	s_or_b64 exec, exec, s[6:7]
	v_add_u32_e32 v88, 0x1440, v102
	v_cmp_ge_i32_e32 vcc, s3, v88
	s_and_saveexec_b64 s[6:7], vcc
	s_cbranch_execz .LBB0_996
	v_add_co_u32_e32 v88, vcc, 0x5000, v2
	s_nop 1
	v_addc_co_u32_e32 v89, vcc, 0, v3, vcc
	global_load_dword v86, v[88:89], off offset:256
.LBB0_996:
	s_or_b64 exec, exec, s[6:7]
	v_add_u32_e32 v88, 0x1480, v102
	v_cmp_ge_i32_e32 vcc, s3, v88
	v_mov_b32_e32 v88, 0
	v_mov_b32_e32 v89, 0
	s_and_saveexec_b64 s[6:7], vcc
	s_cbranch_execz .LBB0_998
	v_add_co_u32_e32 v90, vcc, 0x5000, v2
	s_nop 1
	v_addc_co_u32_e32 v91, vcc, 0, v3, vcc
	global_load_dword v89, v[90:91], off offset:512
.LBB0_998:
	s_or_b64 exec, exec, s[6:7]
	v_add_u32_e32 v90, 0x14c0, v102
	v_cmp_ge_i32_e32 vcc, s3, v90
	s_and_saveexec_b64 s[6:7], vcc
	s_cbranch_execz .LBB0_1000
	v_add_co_u32_e32 v90, vcc, 0x5000, v2
	s_nop 1
	v_addc_co_u32_e32 v91, vcc, 0, v3, vcc
	global_load_dword v88, v[90:91], off offset:768
.LBB0_1000:
	s_or_b64 exec, exec, s[6:7]
	v_add_u32_e32 v90, 0x1500, v102
	v_cmp_ge_i32_e32 vcc, s3, v90
	v_mov_b32_e32 v90, 0
	v_mov_b32_e32 v91, 0
	s_and_saveexec_b64 s[6:7], vcc
	s_cbranch_execz .LBB0_1002
	v_add_co_u32_e32 v92, vcc, 0x5000, v2
	s_nop 1
	v_addc_co_u32_e32 v93, vcc, 0, v3, vcc
	global_load_dword v91, v[92:93], off offset:1024
.LBB0_1002:
	s_or_b64 exec, exec, s[6:7]
	v_add_u32_e32 v92, 0x1540, v102
	v_cmp_ge_i32_e32 vcc, s3, v92
	s_and_saveexec_b64 s[6:7], vcc
	s_cbranch_execz .LBB0_1004
	v_add_co_u32_e32 v92, vcc, 0x5000, v2
	s_nop 1
	v_addc_co_u32_e32 v93, vcc, 0, v3, vcc
	global_load_dword v90, v[92:93], off offset:1280
.LBB0_1004:
	s_or_b64 exec, exec, s[6:7]
	v_add_u32_e32 v92, 0x1580, v102
	v_cmp_ge_i32_e32 vcc, s3, v92
	v_mov_b32_e32 v92, 0
	v_mov_b32_e32 v93, 0
	s_and_saveexec_b64 s[6:7], vcc
	s_cbranch_execz .LBB0_1006
	v_add_co_u32_e32 v94, vcc, 0x5000, v2
	s_nop 1
	v_addc_co_u32_e32 v95, vcc, 0, v3, vcc
	global_load_dword v93, v[94:95], off offset:1536
.LBB0_1006:
	s_or_b64 exec, exec, s[6:7]
	v_add_u32_e32 v94, 0x15c0, v102
	v_cmp_ge_i32_e32 vcc, s3, v94
	s_and_saveexec_b64 s[6:7], vcc
	s_cbranch_execz .LBB0_1008
	v_add_co_u32_e32 v94, vcc, 0x5000, v2
	s_nop 1
	v_addc_co_u32_e32 v95, vcc, 0, v3, vcc
	global_load_dword v92, v[94:95], off offset:1792
.LBB0_1008:
	s_or_b64 exec, exec, s[6:7]
	v_add_u32_e32 v94, 0x1600, v102
	v_cmp_ge_i32_e32 vcc, s3, v94
	v_mov_b32_e32 v94, 0
	v_mov_b32_e32 v95, 0
	s_and_saveexec_b64 s[6:7], vcc
	s_cbranch_execz .LBB0_1010
	v_add_co_u32_e32 v96, vcc, 0x5000, v2
	s_nop 1
	v_addc_co_u32_e32 v97, vcc, 0, v3, vcc
	global_load_dword v95, v[96:97], off offset:2048
.LBB0_1010:
	s_or_b64 exec, exec, s[6:7]
	v_add_u32_e32 v96, 0x1640, v102
	v_cmp_ge_i32_e32 vcc, s3, v96
	s_and_saveexec_b64 s[6:7], vcc
	s_cbranch_execz .LBB0_1012
	v_add_co_u32_e32 v96, vcc, 0x5000, v2
	s_nop 1
	v_addc_co_u32_e32 v97, vcc, 0, v3, vcc
	global_load_dword v94, v[96:97], off offset:2304
.LBB0_1012:
	s_or_b64 exec, exec, s[6:7]
	v_add_u32_e32 v96, 0x1680, v102
	v_cmp_ge_i32_e32 vcc, s3, v96
	v_mov_b32_e32 v96, 0
	v_mov_b32_e32 v97, 0
	s_and_saveexec_b64 s[6:7], vcc
	s_cbranch_execz .LBB0_1014
	v_add_co_u32_e32 v98, vcc, 0x5000, v2
	s_nop 1
	v_addc_co_u32_e32 v99, vcc, 0, v3, vcc
	global_load_dword v97, v[98:99], off offset:2560
.LBB0_1014:
	s_or_b64 exec, exec, s[6:7]
	v_add_u32_e32 v98, 0x16c0, v102
	v_cmp_ge_i32_e32 vcc, s3, v98
	s_and_saveexec_b64 s[6:7], vcc
	s_cbranch_execz .LBB0_1016
	v_add_co_u32_e32 v98, vcc, 0x5000, v2
	s_nop 1
	v_addc_co_u32_e32 v99, vcc, 0, v3, vcc
	global_load_dword v96, v[98:99], off offset:2816
.LBB0_1016:
	s_or_b64 exec, exec, s[6:7]
	v_add_u32_e32 v98, 0x1700, v102
	v_cmp_ge_i32_e32 vcc, s3, v98
	v_mov_b32_e32 v98, 0
	v_mov_b32_e32 v99, 0
	s_and_saveexec_b64 s[6:7], vcc
	s_cbranch_execz .LBB0_1018
	v_add_co_u32_e32 v100, vcc, 0x5000, v2
	s_nop 1
	v_addc_co_u32_e32 v101, vcc, 0, v3, vcc
	global_load_dword v99, v[100:101], off offset:3072
.LBB0_1018:
	s_or_b64 exec, exec, s[6:7]
	v_add_u32_e32 v100, 0x1740, v102
	v_cmp_ge_i32_e32 vcc, s3, v100
	s_and_saveexec_b64 s[6:7], vcc
	s_cbranch_execz .LBB0_1020
	v_add_co_u32_e32 v100, vcc, 0x5000, v2
	s_nop 1
	v_addc_co_u32_e32 v101, vcc, 0, v3, vcc
	global_load_dword v98, v[100:101], off offset:3328
.LBB0_1020:
	s_or_b64 exec, exec, s[6:7]
	v_add_u32_e32 v100, 0x1780, v102
	v_cmp_ge_i32_e32 vcc, s3, v100
	v_mov_b32_e32 v100, 0
	v_mov_b32_e32 v101, 0
	s_and_saveexec_b64 s[6:7], vcc
	s_cbranch_execz .LBB0_1022
	v_add_co_u32_e32 v104, vcc, 0x5000, v2
	s_nop 1
	v_addc_co_u32_e32 v105, vcc, 0, v3, vcc
	global_load_dword v101, v[104:105], off offset:3584
.LBB0_1022:
	s_or_b64 exec, exec, s[6:7]
	v_add_u32_e32 v102, 0x17c0, v102
	v_cmp_ge_i32_e32 vcc, s3, v102
	s_and_saveexec_b64 s[6:7], vcc
	s_cbranch_execz .LBB0_1024
	v_add_co_u32_e32 v102, vcc, 0x5000, v2
	s_nop 1
	v_addc_co_u32_e32 v103, vcc, 0, v3, vcc
	global_load_dword v100, v[102:103], off offset:3840

.LBB0_1025:
	s_cmpk_lt_u32 s3, 0x1bff
	s_mov_b64 s[6:7], -1
	s_cbranch_scc1 .LBB0_1027
	v_add_co_u32_e32 v118, vcc, 0x6000, v2
	s_mov_b64 s[6:7], 0
	s_nop 0
	v_addc_co_u32_e32 v119, vcc, 0, v3, vcc
	global_load_dword v103, v[118:119], off
	global_load_dword v102, v[118:119], off offset:256
	global_load_dword v105, v[118:119], off offset:512
	global_load_dword v104, v[118:119], off offset:768
	global_load_dword v107, v[118:119], off offset:1024
	global_load_dword v106, v[118:119], off offset:1280
	global_load_dword v109, v[118:119], off offset:1536
	global_load_dword v108, v[118:119], off offset:1792
	global_load_dword v111, v[118:119], off offset:2048
	global_load_dword v110, v[118:119], off offset:2304
	global_load_dword v113, v[118:119], off offset:2560
	global_load_dword v112, v[118:119], off offset:2816
	global_load_dword v115, v[118:119], off offset:3072
	global_load_dword v114, v[118:119], off offset:3328
	global_load_dword v117, v[118:119], off offset:3584
	global_load_dword v116, v[118:119], off offset:3840
.LBB0_1027:
	s_andn2_b64 vcc, exec, s[6:7]
	s_cbranch_vccnz .LBB0_1062
	v_mov_b32_e32 v103, 0
	s_cmpk_lt_u32 s3, 0x1800
	v_mov_b32_e32 v102, 0
	v_mov_b32_e32 v105, 0
	v_mov_b32_e32 v104, 0
	v_mov_b32_e32 v107, 0
	v_mov_b32_e32 v106, 0
	v_mov_b32_e32 v109, 0
	v_mov_b32_e32 v108, 0
	v_mov_b32_e32 v111, 0
	v_mov_b32_e32 v110, 0
	v_mov_b32_e32 v113, 0
	v_mov_b32_e32 v112, 0
	v_mov_b32_e32 v115, 0
	v_mov_b32_e32 v114, 0
	v_mov_b32_e32 v117, 0
	v_mov_b32_e32 v116, 0
	s_cbranch_scc1 .LBB0_1062
	v_mov_b32_e32 v118, v30
	v_mov_b32_e32 v103, 0
	v_add_u32_e32 v102, 0x1800, v118
	v_cmp_ge_i32_e32 vcc, s3, v102
	v_mov_b32_e32 v102, 0
	s_and_saveexec_b64 s[6:7], vcc
	s_cbranch_execz .LBB0_1031
	v_add_co_u32_e32 v104, vcc, 0x6000, v2
	s_nop 1
	v_addc_co_u32_e32 v105, vcc, 0, v3, vcc
	global_load_dword v103, v[104:105], off
.LBB0_1031:
	s_or_b64 exec, exec, s[6:7]
	v_add_u32_e32 v104, 0x1840, v118
	v_cmp_ge_i32_e32 vcc, s3, v104
	s_and_saveexec_b64 s[6:7], vcc
	s_cbranch_execz .LBB0_1033
	v_add_co_u32_e32 v104, vcc, 0x6000, v2
	s_nop 1
	v_addc_co_u32_e32 v105, vcc, 0, v3, vcc
	global_load_dword v102, v[104:105], off offset:256
.LBB0_1033:
	s_or_b64 exec, exec, s[6:7]
	v_add_u32_e32 v104, 0x1880, v118
	v_cmp_ge_i32_e32 vcc, s3, v104
	v_mov_b32_e32 v104, 0
	v_mov_b32_e32 v105, 0
	s_and_saveexec_b64 s[6:7], vcc
	s_cbranch_execz .LBB0_1035
	v_add_co_u32_e32 v106, vcc, 0x6000, v2
	s_nop 1
	v_addc_co_u32_e32 v107, vcc, 0, v3, vcc
	global_load_dword v105, v[106:107], off offset:512
.LBB0_1035:
	s_or_b64 exec, exec, s[6:7]
	v_add_u32_e32 v106, 0x18c0, v118
	v_cmp_ge_i32_e32 vcc, s3, v106
	s_and_saveexec_b64 s[6:7], vcc
	s_cbranch_execz .LBB0_1037
	v_add_co_u32_e32 v106, vcc, 0x6000, v2
	s_nop 1
	v_addc_co_u32_e32 v107, vcc, 0, v3, vcc
	global_load_dword v104, v[106:107], off offset:768
.LBB0_1037:
	s_or_b64 exec, exec, s[6:7]
	v_add_u32_e32 v106, 0x1900, v118
	v_cmp_ge_i32_e32 vcc, s3, v106
	v_mov_b32_e32 v106, 0
	v_mov_b32_e32 v107, 0
	s_and_saveexec_b64 s[6:7], vcc
	s_cbranch_execz .LBB0_1039
	v_add_co_u32_e32 v108, vcc, 0x6000, v2
	s_nop 1
	v_addc_co_u32_e32 v109, vcc, 0, v3, vcc
	global_load_dword v107, v[108:109], off offset:1024
.LBB0_1039:
	s_or_b64 exec, exec, s[6:7]
	v_add_u32_e32 v108, 0x1940, v118
	v_cmp_ge_i32_e32 vcc, s3, v108
	s_and_saveexec_b64 s[6:7], vcc
	s_cbranch_execz .LBB0_1041
	v_add_co_u32_e32 v108, vcc, 0x6000, v2
	s_nop 1
	v_addc_co_u32_e32 v109, vcc, 0, v3, vcc
	global_load_dword v106, v[108:109], off offset:1280
.LBB0_1041:
	s_or_b64 exec, exec, s[6:7]
	v_add_u32_e32 v108, 0x1980, v118
	v_cmp_ge_i32_e32 vcc, s3, v108
	v_mov_b32_e32 v108, 0
	v_mov_b32_e32 v109, 0
	s_and_saveexec_b64 s[6:7], vcc
	s_cbranch_execz .LBB0_1043
	v_add_co_u32_e32 v110, vcc, 0x6000, v2
	s_nop 1
	v_addc_co_u32_e32 v111, vcc, 0, v3, vcc
	global_load_dword v109, v[110:111], off offset:1536
.LBB0_1043:
	s_or_b64 exec, exec, s[6:7]
	v_add_u32_e32 v110, 0x19c0, v118
	v_cmp_ge_i32_e32 vcc, s3, v110
	s_and_saveexec_b64 s[6:7], vcc
	s_cbranch_execz .LBB0_1045
	v_add_co_u32_e32 v110, vcc, 0x6000, v2
	s_nop 1
	v_addc_co_u32_e32 v111, vcc, 0, v3, vcc
	global_load_dword v108, v[110:111], off offset:1792
.LBB0_1045:
	s_or_b64 exec, exec, s[6:7]
	v_add_u32_e32 v110, 0x1a00, v118
	v_cmp_ge_i32_e32 vcc, s3, v110
	v_mov_b32_e32 v110, 0
	v_mov_b32_e32 v111, 0
	s_and_saveexec_b64 s[6:7], vcc
	s_cbranch_execz .LBB0_1047
	v_add_co_u32_e32 v112, vcc, 0x6000, v2
	s_nop 1
	v_addc_co_u32_e32 v113, vcc, 0, v3, vcc
	global_load_dword v111, v[112:113], off offset:2048
.LBB0_1047:
	s_or_b64 exec, exec, s[6:7]
	v_add_u32_e32 v112, 0x1a40, v118
	v_cmp_ge_i32_e32 vcc, s3, v112
	s_and_saveexec_b64 s[6:7], vcc
	s_cbranch_execz .LBB0_1049
	v_add_co_u32_e32 v112, vcc, 0x6000, v2
	s_nop 1
	v_addc_co_u32_e32 v113, vcc, 0, v3, vcc
	global_load_dword v110, v[112:113], off offset:2304
.LBB0_1049:
	s_or_b64 exec, exec, s[6:7]
	v_add_u32_e32 v112, 0x1a80, v118
	v_cmp_ge_i32_e32 vcc, s3, v112
	v_mov_b32_e32 v112, 0
	v_mov_b32_e32 v113, 0
	s_and_saveexec_b64 s[6:7], vcc
	s_cbranch_execz .LBB0_1051
	v_add_co_u32_e32 v114, vcc, 0x6000, v2
	s_nop 1
	v_addc_co_u32_e32 v115, vcc, 0, v3, vcc
	global_load_dword v113, v[114:115], off offset:2560
.LBB0_1051:
	s_or_b64 exec, exec, s[6:7]
	v_add_u32_e32 v114, 0x1ac0, v118
	v_cmp_ge_i32_e32 vcc, s3, v114
	s_and_saveexec_b64 s[6:7], vcc
	s_cbranch_execz .LBB0_1053
	v_add_co_u32_e32 v114, vcc, 0x6000, v2
	s_nop 1
	v_addc_co_u32_e32 v115, vcc, 0, v3, vcc
	global_load_dword v112, v[114:115], off offset:2816
.LBB0_1053:
	s_or_b64 exec, exec, s[6:7]
	v_add_u32_e32 v114, 0x1b00, v118
	v_cmp_ge_i32_e32 vcc, s3, v114
	v_mov_b32_e32 v114, 0
	v_mov_b32_e32 v115, 0
	s_and_saveexec_b64 s[6:7], vcc
	s_cbranch_execz .LBB0_1055
	v_add_co_u32_e32 v116, vcc, 0x6000, v2
	s_nop 1
	v_addc_co_u32_e32 v117, vcc, 0, v3, vcc
	global_load_dword v115, v[116:117], off offset:3072
.LBB0_1055:
	s_or_b64 exec, exec, s[6:7]
	v_add_u32_e32 v116, 0x1b40, v118
	v_cmp_ge_i32_e32 vcc, s3, v116
	s_and_saveexec_b64 s[6:7], vcc
	s_cbranch_execz .LBB0_1057
	v_add_co_u32_e32 v116, vcc, 0x6000, v2
	s_nop 1
	v_addc_co_u32_e32 v117, vcc, 0, v3, vcc
	global_load_dword v114, v[116:117], off offset:3328
.LBB0_1057:
	s_or_b64 exec, exec, s[6:7]
	v_add_u32_e32 v116, 0x1b80, v118
	v_cmp_ge_i32_e32 vcc, s3, v116
	v_mov_b32_e32 v116, 0
	v_mov_b32_e32 v117, 0
	s_and_saveexec_b64 s[6:7], vcc
	s_cbranch_execz .LBB0_1059
	v_add_co_u32_e32 v120, vcc, 0x6000, v2
	s_nop 1
	v_addc_co_u32_e32 v121, vcc, 0, v3, vcc
	global_load_dword v117, v[120:121], off offset:3584
.LBB0_1059:
	s_or_b64 exec, exec, s[6:7]
	v_add_u32_e32 v118, 0x1bc0, v118
	v_cmp_ge_i32_e32 vcc, s3, v118
	s_and_saveexec_b64 s[6:7], vcc
	s_cbranch_execz .LBB0_1061
	v_add_co_u32_e32 v118, vcc, 0x6000, v2
	s_nop 1
	v_addc_co_u32_e32 v119, vcc, 0, v3, vcc
	global_load_dword v116, v[118:119], off offset:3840

.LBB0_1062:
	s_cmpk_lt_u32 s3, 0x1fff
	s_mov_b64 s[6:7], -1
	s_cbranch_scc1 .LBB0_1064
	v_add_co_u32_e32 v134, vcc, 0x7000, v2
	s_mov_b64 s[6:7], 0
	s_nop 0
	v_addc_co_u32_e32 v135, vcc, 0, v3, vcc
	global_load_dword v119, v[134:135], off
	global_load_dword v118, v[134:135], off offset:256
	global_load_dword v123, v[134:135], off offset:512
	global_load_dword v120, v[134:135], off offset:768
	global_load_dword v125, v[134:135], off offset:1024
	global_load_dword v121, v[134:135], off offset:1280
	global_load_dword v127, v[134:135], off offset:1536
	global_load_dword v122, v[134:135], off offset:1792
	global_load_dword v129, v[134:135], off offset:2048
	global_load_dword v124, v[134:135], off offset:2304
	global_load_dword v131, v[134:135], off offset:2560
	global_load_dword v126, v[134:135], off offset:2816
	global_load_dword v132, v[134:135], off offset:3072
	global_load_dword v128, v[134:135], off offset:3328
	global_load_dword v133, v[134:135], off offset:3584
	global_load_dword v130, v[134:135], off offset:3840
.LBB0_1064:
	s_andn2_b64 vcc, exec, s[6:7]
	s_cbranch_vccnz .LBB0_1099
	v_mov_b32_e32 v130, 0
	s_cmpk_lt_u32 s3, 0x1c00
	v_mov_b32_e32 v133, 0
	v_mov_b32_e32 v128, 0
	v_mov_b32_e32 v132, 0
	v_mov_b32_e32 v126, 0
	v_mov_b32_e32 v131, 0
	v_mov_b32_e32 v124, 0
	v_mov_b32_e32 v129, 0
	v_mov_b32_e32 v122, 0
	v_mov_b32_e32 v127, 0
	v_mov_b32_e32 v121, 0
	v_mov_b32_e32 v125, 0
	v_mov_b32_e32 v119, 0
	v_mov_b32_e32 v118, 0
	v_mov_b32_e32 v123, 0
	v_mov_b32_e32 v120, 0
	s_cbranch_scc1 .LBB0_1099
	v_mov_b32_e32 v134, v30
	v_mov_b32_e32 v119, 0
	v_add_u32_e32 v118, 0x1c00, v134
	v_cmp_ge_i32_e32 vcc, s3, v118
	v_mov_b32_e32 v118, 0
	s_and_saveexec_b64 s[6:7], vcc
	s_cbranch_execz .LBB0_1068
	v_add_co_u32_e32 v120, vcc, 0x7000, v2
	s_nop 1
	v_addc_co_u32_e32 v121, vcc, 0, v3, vcc
	global_load_dword v119, v[120:121], off
.LBB0_1068:
	s_or_b64 exec, exec, s[6:7]
	v_add_u32_e32 v120, 0x1c40, v134
	v_cmp_ge_i32_e32 vcc, s3, v120
	s_and_saveexec_b64 s[6:7], vcc
	s_cbranch_execz .LBB0_1070
	v_add_co_u32_e32 v120, vcc, 0x7000, v2
	s_nop 1
	v_addc_co_u32_e32 v121, vcc, 0, v3, vcc
	global_load_dword v118, v[120:121], off offset:256
.LBB0_1070:
	s_or_b64 exec, exec, s[6:7]
	v_add_u32_e32 v120, 0x1c80, v134
	v_cmp_ge_i32_e32 vcc, s3, v120
	v_mov_b32_e32 v120, 0
	v_mov_b32_e32 v123, 0
	s_and_saveexec_b64 s[6:7], vcc
	s_cbranch_execz .LBB0_1072
	v_add_co_u32_e32 v122, vcc, 0x7000, v2
	s_nop 1
	v_addc_co_u32_e32 v123, vcc, 0, v3, vcc
	global_load_dword v123, v[122:123], off offset:512
.LBB0_1072:
	s_or_b64 exec, exec, s[6:7]
	v_add_u32_e32 v121, 0x1cc0, v134
	v_cmp_ge_i32_e32 vcc, s3, v121
	s_and_saveexec_b64 s[6:7], vcc
	s_cbranch_execz .LBB0_1074
	v_add_co_u32_e32 v120, vcc, 0x7000, v2
	s_nop 1
	v_addc_co_u32_e32 v121, vcc, 0, v3, vcc
	global_load_dword v120, v[120:121], off offset:768
.LBB0_1074:
	s_or_b64 exec, exec, s[6:7]
	v_add_u32_e32 v121, 0x1d00, v134
	v_cmp_ge_i32_e32 vcc, s3, v121
	v_mov_b32_e32 v121, 0
	v_mov_b32_e32 v125, 0
	s_and_saveexec_b64 s[6:7], vcc
	s_cbranch_execz .LBB0_1076
	v_add_co_u32_e32 v124, vcc, 0x7000, v2
	s_nop 1
	v_addc_co_u32_e32 v125, vcc, 0, v3, vcc
	global_load_dword v125, v[124:125], off offset:1024
.LBB0_1076:
	s_or_b64 exec, exec, s[6:7]
	v_add_u32_e32 v122, 0x1d40, v134
	v_cmp_ge_i32_e32 vcc, s3, v122
	s_and_saveexec_b64 s[6:7], vcc
	s_cbranch_execz .LBB0_1078
	v_add_co_u32_e32 v126, vcc, 0x7000, v2
	s_nop 1
	v_addc_co_u32_e32 v127, vcc, 0, v3, vcc
	global_load_dword v121, v[126:127], off offset:1280
.LBB0_1078:
	s_or_b64 exec, exec, s[6:7]
	v_add_u32_e32 v122, 0x1d80, v134
	v_cmp_ge_i32_e32 vcc, s3, v122
	v_mov_b32_e32 v122, 0
	v_mov_b32_e32 v127, 0
	s_and_saveexec_b64 s[6:7], vcc
	s_cbranch_execz .LBB0_1080
	v_add_co_u32_e32 v126, vcc, 0x7000, v2
	s_nop 1
	v_addc_co_u32_e32 v127, vcc, 0, v3, vcc
	global_load_dword v127, v[126:127], off offset:1536
.LBB0_1080:
	s_or_b64 exec, exec, s[6:7]
	v_add_u32_e32 v124, 0x1dc0, v134
	v_cmp_ge_i32_e32 vcc, s3, v124
	s_and_saveexec_b64 s[6:7], vcc
	s_cbranch_execz .LBB0_1082
	v_add_co_u32_e32 v128, vcc, 0x7000, v2
	s_nop 1
	v_addc_co_u32_e32 v129, vcc, 0, v3, vcc
	global_load_dword v122, v[128:129], off offset:1792
.LBB0_1082:
	s_or_b64 exec, exec, s[6:7]
	v_add_u32_e32 v124, 0x1e00, v134
	v_cmp_ge_i32_e32 vcc, s3, v124
	v_mov_b32_e32 v124, 0
	v_mov_b32_e32 v129, 0
	s_and_saveexec_b64 s[6:7], vcc
	s_cbranch_execz .LBB0_1084
	v_add_co_u32_e32 v128, vcc, 0x7000, v2
	s_nop 1
	v_addc_co_u32_e32 v129, vcc, 0, v3, vcc
	global_load_dword v129, v[128:129], off offset:2048
.LBB0_1084:
	s_or_b64 exec, exec, s[6:7]
	v_add_u32_e32 v126, 0x1e40, v134
	v_cmp_ge_i32_e32 vcc, s3, v126
	s_and_saveexec_b64 s[6:7], vcc
	s_cbranch_execz .LBB0_1086
	v_add_co_u32_e32 v130, vcc, 0x7000, v2
	s_nop 1
	v_addc_co_u32_e32 v131, vcc, 0, v3, vcc
	global_load_dword v124, v[130:131], off offset:2304
.LBB0_1086:
	s_or_b64 exec, exec, s[6:7]
	v_add_u32_e32 v126, 0x1e80, v134
	v_cmp_ge_i32_e32 vcc, s3, v126
	v_mov_b32_e32 v126, 0
	v_mov_b32_e32 v131, 0
	s_and_saveexec_b64 s[6:7], vcc
	s_cbranch_execz .LBB0_1088
	v_add_co_u32_e32 v130, vcc, 0x7000, v2
	s_nop 1
	v_addc_co_u32_e32 v131, vcc, 0, v3, vcc
	global_load_dword v131, v[130:131], off offset:2560
.LBB0_1088:
	s_or_b64 exec, exec, s[6:7]
	v_add_u32_e32 v128, 0x1ec0, v134
	v_cmp_ge_i32_e32 vcc, s3, v128
	s_and_saveexec_b64 s[6:7], vcc
	s_cbranch_execz .LBB0_1090
	v_add_co_u32_e32 v132, vcc, 0x7000, v2
	s_nop 1
	v_addc_co_u32_e32 v133, vcc, 0, v3, vcc
	global_load_dword v126, v[132:133], off offset:2816
.LBB0_1090:
	s_or_b64 exec, exec, s[6:7]
	v_add_u32_e32 v128, 0x1f00, v134
	v_cmp_ge_i32_e32 vcc, s3, v128
	v_mov_b32_e32 v128, 0
	v_mov_b32_e32 v132, 0
	s_and_saveexec_b64 s[6:7], vcc
	s_cbranch_execz .LBB0_1092
	v_add_co_u32_e32 v132, vcc, 0x7000, v2
	s_nop 1
	v_addc_co_u32_e32 v133, vcc, 0, v3, vcc
	global_load_dword v132, v[132:133], off offset:3072
.LBB0_1092:
	s_or_b64 exec, exec, s[6:7]
	v_add_u32_e32 v130, 0x1f40, v134
	v_cmp_ge_i32_e32 vcc, s3, v130
	s_and_saveexec_b64 s[6:7], vcc
	s_cbranch_execz .LBB0_1094
	v_add_co_u32_e32 v136, vcc, 0x7000, v2
	s_nop 1
	v_addc_co_u32_e32 v137, vcc, 0, v3, vcc
	global_load_dword v128, v[136:137], off offset:3328
.LBB0_1094:
	s_or_b64 exec, exec, s[6:7]
	v_add_u32_e32 v130, 0x1f80, v134
	v_cmp_ge_i32_e32 vcc, s3, v130
	v_mov_b32_e32 v130, 0
	v_mov_b32_e32 v133, 0
	s_and_saveexec_b64 s[6:7], vcc
	s_cbranch_execz .LBB0_1096
	v_add_co_u32_e32 v136, vcc, 0x7000, v2
	s_nop 1
	v_addc_co_u32_e32 v137, vcc, 0, v3, vcc
	global_load_dword v133, v[136:137], off offset:3584
.LBB0_1096:
	s_or_b64 exec, exec, s[6:7]
	v_add_u32_e32 v134, 0x1fc0, v134
	v_cmp_ge_i32_e32 vcc, s3, v134
	s_and_saveexec_b64 s[6:7], vcc
	s_cbranch_execz .LBB0_1098
	v_add_co_u32_e32 v2, vcc, 0x7000, v2
	s_nop 1
	v_addc_co_u32_e32 v3, vcc, 0, v3, vcc
	global_load_dword v130, v[2:3], off offset:3840

.LBB0_3062:
	s_or_b32 s0, s93, s20
	s_add_i32 s61, s21, s93
	s_ashr_i32 s1, s0, 31
	s_add_i32 s56, s61, 1
	s_lshl_b64 s[0:1], s[0:1], 15
	v_and_b32_e32 v30, 63, v0
	s_add_u32 s0, s62, s0
	s_addc_u32 s1, s63, s1
	v_ashrrev_i32_e32 v31, 31, v30
	v_lshl_add_u64 v[2:3], v[30:31], 2, s[0:1]
	s_cmpk_gt_i32 s61, 0xff
	s_mov_b64 s[0:1], -1
	s_cbranch_scc0 .LBB0_4440
	s_cmpk_lt_u32 s61, 0x3ff
	s_cbranch_scc1 .LBB0_3067
	global_load_dword v19, v[2:3], off
	global_load_dword v13, v[2:3], off offset:256
	global_load_dword v20, v[2:3], off offset:512
	global_load_dword v12, v[2:3], off offset:768
	global_load_dword v18, v[2:3], off offset:1024
	global_load_dword v10, v[2:3], off offset:1280
	global_load_dword v17, v[2:3], off offset:1536
	global_load_dword v9, v[2:3], off offset:1792
	global_load_dword v16, v[2:3], off offset:2048
	global_load_dword v8, v[2:3], off offset:2304
	global_load_dword v15, v[2:3], off offset:2560
	global_load_dword v7, v[2:3], off offset:2816
	global_load_dword v14, v[2:3], off offset:3072
	global_load_dword v5, v[2:3], off offset:3328
	global_load_dword v11, v[2:3], off offset:3584
	global_load_dword v4, v[2:3], off offset:3840
	s_movk_i32 s2, 0x300
	s_cbranch_execz .LBB0_3068

.LBB0_3068:
	v_mov_b32_e32 v21, v30
	v_mov_b32_e32 v13, 0
	v_cmp_ge_i32_e32 vcc, s61, v21
	v_mov_b32_e32 v19, 0
	s_and_saveexec_b64 s[0:1], vcc
	s_cbranch_execz .LBB0_3070
	global_load_dword v19, v[2:3], off
.LBB0_3070:
	s_or_b64 exec, exec, s[0:1]
	v_add_u32_e32 v4, 64, v21
	v_cmp_ge_i32_e32 vcc, s61, v4
	s_and_saveexec_b64 s[0:1], vcc
	s_cbranch_execz .LBB0_3072
	global_load_dword v13, v[2:3], off offset:256
.LBB0_3072:
	s_or_b64 exec, exec, s[0:1]
	v_add_u32_e32 v4, 0x80, v21
	v_cmp_ge_i32_e32 vcc, s61, v4
	v_mov_b32_e32 v12, 0
	v_mov_b32_e32 v20, 0
	s_and_saveexec_b64 s[0:1], vcc
	s_cbranch_execz .LBB0_3074
	global_load_dword v20, v[2:3], off offset:512
.LBB0_3074:
	s_or_b64 exec, exec, s[0:1]
	v_add_u32_e32 v4, 0xc0, v21
	v_cmp_ge_i32_e32 vcc, s61, v4
	s_and_saveexec_b64 s[0:1], vcc
	s_cbranch_execz .LBB0_3076
	global_load_dword v12, v[2:3], off offset:768
.LBB0_3076:
	s_or_b64 exec, exec, s[0:1]
	v_add_u32_e32 v4, 0x100, v21
	v_cmp_ge_i32_e32 vcc, s61, v4
	v_mov_b32_e32 v10, 0
	v_mov_b32_e32 v18, 0
	s_and_saveexec_b64 s[0:1], vcc
	s_cbranch_execz .LBB0_3078
	global_load_dword v18, v[2:3], off offset:1024
.LBB0_3078:
	s_or_b64 exec, exec, s[0:1]
	v_add_u32_e32 v4, 0x140, v21
	v_cmp_ge_i32_e32 vcc, s61, v4
	s_and_saveexec_b64 s[0:1], vcc
	s_cbranch_execz .LBB0_3080
	global_load_dword v10, v[2:3], off offset:1280
.LBB0_3080:
	s_or_b64 exec, exec, s[0:1]
	v_add_u32_e32 v4, 0x180, v21
	v_cmp_ge_i32_e32 vcc, s61, v4
	v_mov_b32_e32 v9, 0
	v_mov_b32_e32 v17, 0
	s_and_saveexec_b64 s[0:1], vcc
	s_cbranch_execz .LBB0_3082
	global_load_dword v17, v[2:3], off offset:1536
.LBB0_3082:
	s_or_b64 exec, exec, s[0:1]
	v_add_u32_e32 v4, 0x1c0, v21
	v_cmp_ge_i32_e32 vcc, s61, v4
	s_and_saveexec_b64 s[0:1], vcc
	s_cbranch_execz .LBB0_3084
	global_load_dword v9, v[2:3], off offset:1792
.LBB0_3084:
	s_or_b64 exec, exec, s[0:1]
	v_add_u32_e32 v4, 0x200, v21
	v_cmp_ge_i32_e32 vcc, s61, v4
	v_mov_b32_e32 v8, 0
	v_mov_b32_e32 v16, 0
	s_and_saveexec_b64 s[0:1], vcc
	s_cbranch_execz .LBB0_3086
	global_load_dword v16, v[2:3], off offset:2048
.LBB0_3086:
	s_or_b64 exec, exec, s[0:1]
	v_add_u32_e32 v4, 0x240, v21
	v_cmp_ge_i32_e32 vcc, s61, v4
	s_and_saveexec_b64 s[0:1], vcc
	s_cbranch_execz .LBB0_3088
	global_load_dword v8, v[2:3], off offset:2304
.LBB0_3088:
	s_or_b64 exec, exec, s[0:1]
	v_add_u32_e32 v4, 0x280, v21
	v_cmp_ge_i32_e32 vcc, s61, v4
	v_mov_b32_e32 v7, 0
	v_mov_b32_e32 v15, 0
	s_and_saveexec_b64 s[0:1], vcc
	s_cbranch_execz .LBB0_3090
	global_load_dword v15, v[2:3], off offset:2560
.LBB0_3090:
	s_or_b64 exec, exec, s[0:1]
	v_add_u32_e32 v4, 0x2c0, v21
	v_cmp_ge_i32_e32 vcc, s61, v4
	s_and_saveexec_b64 s[0:1], vcc
	s_cbranch_execz .LBB0_3092
	global_load_dword v7, v[2:3], off offset:2816
.LBB0_3092:
	s_or_b64 exec, exec, s[0:1]
	v_add_u32_e32 v4, 0x300, v21
	v_cmp_ge_i32_e32 vcc, s61, v4
	v_mov_b32_e32 v5, 0
	v_mov_b32_e32 v14, 0
	s_and_saveexec_b64 s[0:1], vcc
	s_cbranch_execz .LBB0_3094
	global_load_dword v14, v[2:3], off offset:3072
.LBB0_3094:
	s_or_b64 exec, exec, s[0:1]
	v_add_u32_e32 v4, 0x340, v21
	v_cmp_ge_i32_e32 vcc, s61, v4
	s_and_saveexec_b64 s[0:1], vcc
	s_cbranch_execz .LBB0_3096
	global_load_dword v5, v[2:3], off offset:3328
.LBB0_3096:
	s_or_b64 exec, exec, s[0:1]
	v_add_u32_e32 v4, 0x380, v21
	v_cmp_ge_i32_e32 vcc, s61, v4
	v_mov_b32_e32 v4, 0
	v_mov_b32_e32 v11, 0
	s_and_saveexec_b64 s[0:1], vcc
	s_cbranch_execz .LBB0_3098
	global_load_dword v11, v[2:3], off offset:3584
.LBB0_3098:
	s_or_b64 exec, exec, s[0:1]
	v_add_u32_e32 v21, 0x3c0, v21
	v_cmp_ge_i32_e32 vcc, s61, v21
	s_and_saveexec_b64 s[0:1], vcc
	s_cbranch_execz .LBB0_3100
	global_load_dword v4, v[2:3], off offset:3840

.LBB0_3102:
	v_mov_b32_e32 v22, 0
	s_cmpk_lt_u32 s61, 0x400
	v_mov_b32_e32 v21, 0
	v_mov_b32_e32 v24, 0
	v_mov_b32_e32 v23, 0
	v_mov_b32_e32 v26, 0
	v_mov_b32_e32 v25, 0
	v_mov_b32_e32 v28, 0
	v_mov_b32_e32 v27, 0
	v_mov_b32_e32 v31, 0
	v_mov_b32_e32 v29, 0
	v_mov_b32_e32 v33, 0
	v_mov_b32_e32 v32, 0
	v_mov_b32_e32 v35, 0
	v_mov_b32_e32 v34, 0
	v_mov_b32_e32 v37, 0
	v_mov_b32_e32 v36, 0
	s_cbranch_scc1 .LBB0_3136
	v_mov_b32_e32 v38, v30
	v_mov_b32_e32 v22, 0
	v_add_u32_e32 v21, 0x400, v38
	v_cmp_ge_i32_e32 vcc, s61, v21
	v_mov_b32_e32 v21, 0
	s_and_saveexec_b64 s[0:1], vcc
	s_cbranch_execz .LBB0_3105
	v_add_co_u32_e32 v22, vcc, 0x1000, v2
	s_nop 1
	v_addc_co_u32_e32 v23, vcc, 0, v3, vcc
	global_load_dword v22, v[22:23], off
.LBB0_3105:
	s_or_b64 exec, exec, s[0:1]
	v_add_u32_e32 v23, 0x440, v38
	v_cmp_ge_i32_e32 vcc, s61, v23
	s_and_saveexec_b64 s[0:1], vcc
	s_cbranch_execz .LBB0_3107
	v_add_co_u32_e32 v24, vcc, 0x1000, v2
	s_nop 1
	v_addc_co_u32_e32 v25, vcc, 0, v3, vcc
	global_load_dword v21, v[24:25], off offset:256
.LBB0_3107:
	s_or_b64 exec, exec, s[0:1]
	v_add_u32_e32 v23, 0x480, v38
	v_cmp_ge_i32_e32 vcc, s61, v23
	v_mov_b32_e32 v23, 0
	v_mov_b32_e32 v24, 0
	s_and_saveexec_b64 s[0:1], vcc
	s_cbranch_execz .LBB0_3109
	v_add_co_u32_e32 v24, vcc, 0x1000, v2
	s_nop 1
	v_addc_co_u32_e32 v25, vcc, 0, v3, vcc
	global_load_dword v24, v[24:25], off offset:512
.LBB0_3109:
	s_or_b64 exec, exec, s[0:1]
	v_add_u32_e32 v25, 0x4c0, v38
	v_cmp_ge_i32_e32 vcc, s61, v25
	s_and_saveexec_b64 s[0:1], vcc
	s_cbranch_execz .LBB0_3111
	v_add_co_u32_e32 v26, vcc, 0x1000, v2
	s_nop 1
	v_addc_co_u32_e32 v27, vcc, 0, v3, vcc
	global_load_dword v23, v[26:27], off offset:768
.LBB0_3111:
	s_or_b64 exec, exec, s[0:1]
	v_add_u32_e32 v25, 0x500, v38
	v_cmp_ge_i32_e32 vcc, s61, v25
	v_mov_b32_e32 v25, 0
	v_mov_b32_e32 v26, 0
	s_and_saveexec_b64 s[0:1], vcc
	s_cbranch_execz .LBB0_3113
	v_add_co_u32_e32 v26, vcc, 0x1000, v2
	s_nop 1
	v_addc_co_u32_e32 v27, vcc, 0, v3, vcc
	global_load_dword v26, v[26:27], off offset:1024
.LBB0_3113:
	s_or_b64 exec, exec, s[0:1]
	v_add_u32_e32 v27, 0x540, v38
	v_cmp_ge_i32_e32 vcc, s61, v27
	s_and_saveexec_b64 s[0:1], vcc
	s_cbranch_execz .LBB0_3115
	v_add_co_u32_e32 v28, vcc, 0x1000, v2
	s_nop 1
	v_addc_co_u32_e32 v29, vcc, 0, v3, vcc
	global_load_dword v25, v[28:29], off offset:1280
.LBB0_3115:
	s_or_b64 exec, exec, s[0:1]
	v_add_u32_e32 v27, 0x580, v38
	v_cmp_ge_i32_e32 vcc, s61, v27
	v_mov_b32_e32 v27, 0
	v_mov_b32_e32 v28, 0
	s_and_saveexec_b64 s[0:1], vcc
	s_cbranch_execz .LBB0_3117
	v_add_co_u32_e32 v28, vcc, 0x1000, v2
	s_nop 1
	v_addc_co_u32_e32 v29, vcc, 0, v3, vcc
	global_load_dword v28, v[28:29], off offset:1536
.LBB0_3117:
	s_or_b64 exec, exec, s[0:1]
	v_add_u32_e32 v29, 0x5c0, v38
	v_cmp_ge_i32_e32 vcc, s61, v29
	s_and_saveexec_b64 s[0:1], vcc
	s_cbranch_execz .LBB0_3119
	v_add_co_u32_e32 v32, vcc, 0x1000, v2
	s_nop 1
	v_addc_co_u32_e32 v33, vcc, 0, v3, vcc
	global_load_dword v27, v[32:33], off offset:1792
.LBB0_3119:
	s_or_b64 exec, exec, s[0:1]
	v_add_u32_e32 v29, 0x600, v38
	v_cmp_ge_i32_e32 vcc, s61, v29
	v_mov_b32_e32 v29, 0
	v_mov_b32_e32 v31, 0
	s_and_saveexec_b64 s[0:1], vcc
	s_cbranch_execz .LBB0_3121
	v_add_co_u32_e32 v32, vcc, 0x1000, v2
	s_nop 1
	v_addc_co_u32_e32 v33, vcc, 0, v3, vcc
	global_load_dword v31, v[32:33], off offset:2048
.LBB0_3121:
	s_or_b64 exec, exec, s[0:1]
	v_add_u32_e32 v32, 0x640, v38
	v_cmp_ge_i32_e32 vcc, s61, v32
	s_and_saveexec_b64 s[0:1], vcc
	s_cbranch_execz .LBB0_3123
	v_add_co_u32_e32 v32, vcc, 0x1000, v2
	s_nop 1
	v_addc_co_u32_e32 v33, vcc, 0, v3, vcc
	global_load_dword v29, v[32:33], off offset:2304
.LBB0_3123:
	s_or_b64 exec, exec, s[0:1]
	v_add_u32_e32 v32, 0x680, v38
	v_cmp_ge_i32_e32 vcc, s61, v32
	v_mov_b32_e32 v32, 0
	v_mov_b32_e32 v33, 0
	s_and_saveexec_b64 s[0:1], vcc
	s_cbranch_execz .LBB0_3125
	v_add_co_u32_e32 v34, vcc, 0x1000, v2
	s_nop 1
	v_addc_co_u32_e32 v35, vcc, 0, v3, vcc
	global_load_dword v33, v[34:35], off offset:2560
.LBB0_3125:
	s_or_b64 exec, exec, s[0:1]
	v_add_u32_e32 v34, 0x6c0, v38
	v_cmp_ge_i32_e32 vcc, s61, v34
	s_and_saveexec_b64 s[0:1], vcc
	s_cbranch_execz .LBB0_3127
	v_add_co_u32_e32 v34, vcc, 0x1000, v2
	s_nop 1
	v_addc_co_u32_e32 v35, vcc, 0, v3, vcc
	global_load_dword v32, v[34:35], off offset:2816
.LBB0_3127:
	s_or_b64 exec, exec, s[0:1]
	v_add_u32_e32 v34, 0x700, v38
	v_cmp_ge_i32_e32 vcc, s61, v34
	v_mov_b32_e32 v34, 0
	v_mov_b32_e32 v35, 0
	s_and_saveexec_b64 s[0:1], vcc
	s_cbranch_execz .LBB0_3129
	v_add_co_u32_e32 v36, vcc, 0x1000, v2
	s_nop 1
	v_addc_co_u32_e32 v37, vcc, 0, v3, vcc
	global_load_dword v35, v[36:37], off offset:3072
.LBB0_3129:
	s_or_b64 exec, exec, s[0:1]
	v_add_u32_e32 v36, 0x740, v38
	v_cmp_ge_i32_e32 vcc, s61, v36
	s_and_saveexec_b64 s[0:1], vcc
	s_cbranch_execz .LBB0_3131
	v_add_co_u32_e32 v36, vcc, 0x1000, v2
	s_nop 1
	v_addc_co_u32_e32 v37, vcc, 0, v3, vcc
	global_load_dword v34, v[36:37], off offset:3328
.LBB0_3131:
	s_or_b64 exec, exec, s[0:1]
	v_add_u32_e32 v36, 0x780, v38
	v_cmp_ge_i32_e32 vcc, s61, v36
	v_mov_b32_e32 v36, 0
	v_mov_b32_e32 v37, 0
	s_and_saveexec_b64 s[0:1], vcc
	s_cbranch_execz .LBB0_3133
	v_add_co_u32_e32 v40, vcc, 0x1000, v2
	s_nop 1
	v_addc_co_u32_e32 v41, vcc, 0, v3, vcc
	global_load_dword v37, v[40:41], off offset:3584
.LBB0_3133:
	s_or_b64 exec, exec, s[0:1]
	v_add_u32_e32 v38, 0x7c0, v38
	v_cmp_ge_i32_e32 vcc, s61, v38
	s_and_saveexec_b64 s[0:1], vcc
	s_cbranch_execz .LBB0_3135
	v_add_co_u32_e32 v38, vcc, 0x1000, v2
	s_nop 1
	v_addc_co_u32_e32 v39, vcc, 0, v3, vcc
	global_load_dword v36, v[38:39], off offset:3840

.LBB0_3136:
	s_cmpk_lt_u32 s61, 0xbff
	s_mov_b64 s[0:1], -1
	s_cbranch_scc1 .LBB0_3138
	v_add_co_u32_e32 v54, vcc, 0x2000, v2
	s_mov_b64 s[0:1], 0
	s_nop 0
	v_addc_co_u32_e32 v55, vcc, 0, v3, vcc
	global_load_dword v39, v[54:55], off
	global_load_dword v38, v[54:55], off offset:256
	global_load_dword v41, v[54:55], off offset:512
	global_load_dword v40, v[54:55], off offset:768
	global_load_dword v43, v[54:55], off offset:1024
	global_load_dword v42, v[54:55], off offset:1280
	global_load_dword v45, v[54:55], off offset:1536
	global_load_dword v44, v[54:55], off offset:1792
	global_load_dword v47, v[54:55], off offset:2048
	global_load_dword v46, v[54:55], off offset:2304
	global_load_dword v49, v[54:55], off offset:2560
	global_load_dword v48, v[54:55], off offset:2816
	global_load_dword v51, v[54:55], off offset:3072
	global_load_dword v50, v[54:55], off offset:3328
	global_load_dword v53, v[54:55], off offset:3584
	global_load_dword v52, v[54:55], off offset:3840
.LBB0_3138:
	s_andn2_b64 vcc, exec, s[0:1]
	s_cbranch_vccnz .LBB0_3173
	v_mov_b32_e32 v39, 0
	s_cmpk_lt_u32 s61, 0x800
	v_mov_b32_e32 v38, 0
	v_mov_b32_e32 v41, 0
	v_mov_b32_e32 v40, 0
	v_mov_b32_e32 v43, 0
	v_mov_b32_e32 v42, 0
	v_mov_b32_e32 v45, 0
	v_mov_b32_e32 v44, 0
	v_mov_b32_e32 v47, 0
	v_mov_b32_e32 v46, 0
	v_mov_b32_e32 v49, 0
	v_mov_b32_e32 v48, 0
	v_mov_b32_e32 v51, 0
	v_mov_b32_e32 v50, 0
	v_mov_b32_e32 v53, 0
	v_mov_b32_e32 v52, 0
	s_cbranch_scc1 .LBB0_3173
	v_mov_b32_e32 v54, v30
	v_mov_b32_e32 v39, 0
	v_add_u32_e32 v38, 0x800, v54
	v_cmp_ge_i32_e32 vcc, s61, v38
	v_mov_b32_e32 v38, 0
	s_and_saveexec_b64 s[0:1], vcc
	s_cbranch_execz .LBB0_3142
	v_add_co_u32_e32 v40, vcc, 0x2000, v2
	s_nop 1
	v_addc_co_u32_e32 v41, vcc, 0, v3, vcc
	global_load_dword v39, v[40:41], off
.LBB0_3142:
	s_or_b64 exec, exec, s[0:1]
	v_add_u32_e32 v40, 0x840, v54
	v_cmp_ge_i32_e32 vcc, s61, v40
	s_and_saveexec_b64 s[0:1], vcc
	s_cbranch_execz .LBB0_3144
	v_add_co_u32_e32 v40, vcc, 0x2000, v2
	s_nop 1
	v_addc_co_u32_e32 v41, vcc, 0, v3, vcc
	global_load_dword v38, v[40:41], off offset:256
.LBB0_3144:
	s_or_b64 exec, exec, s[0:1]
	v_add_u32_e32 v40, 0x880, v54
	v_cmp_ge_i32_e32 vcc, s61, v40
	v_mov_b32_e32 v40, 0
	v_mov_b32_e32 v41, 0
	s_and_saveexec_b64 s[0:1], vcc
	s_cbranch_execz .LBB0_3146
	v_add_co_u32_e32 v42, vcc, 0x2000, v2
	s_nop 1
	v_addc_co_u32_e32 v43, vcc, 0, v3, vcc
	global_load_dword v41, v[42:43], off offset:512
.LBB0_3146:
	s_or_b64 exec, exec, s[0:1]
	v_add_u32_e32 v42, 0x8c0, v54
	v_cmp_ge_i32_e32 vcc, s61, v42
	s_and_saveexec_b64 s[0:1], vcc
	s_cbranch_execz .LBB0_3148
	v_add_co_u32_e32 v42, vcc, 0x2000, v2
	s_nop 1
	v_addc_co_u32_e32 v43, vcc, 0, v3, vcc
	global_load_dword v40, v[42:43], off offset:768
.LBB0_3148:
	s_or_b64 exec, exec, s[0:1]
	v_add_u32_e32 v42, 0x900, v54
	v_cmp_ge_i32_e32 vcc, s61, v42
	v_mov_b32_e32 v42, 0
	v_mov_b32_e32 v43, 0
	s_and_saveexec_b64 s[0:1], vcc
	s_cbranch_execz .LBB0_3150
	v_add_co_u32_e32 v44, vcc, 0x2000, v2
	s_nop 1
	v_addc_co_u32_e32 v45, vcc, 0, v3, vcc
	global_load_dword v43, v[44:45], off offset:1024
.LBB0_3150:
	s_or_b64 exec, exec, s[0:1]
	v_add_u32_e32 v44, 0x940, v54
	v_cmp_ge_i32_e32 vcc, s61, v44
	s_and_saveexec_b64 s[0:1], vcc
	s_cbranch_execz .LBB0_3152
	v_add_co_u32_e32 v44, vcc, 0x2000, v2
	s_nop 1
	v_addc_co_u32_e32 v45, vcc, 0, v3, vcc
	global_load_dword v42, v[44:45], off offset:1280
.LBB0_3152:
	s_or_b64 exec, exec, s[0:1]
	v_add_u32_e32 v44, 0x980, v54
	v_cmp_ge_i32_e32 vcc, s61, v44
	v_mov_b32_e32 v44, 0
	v_mov_b32_e32 v45, 0
	s_and_saveexec_b64 s[0:1], vcc
	s_cbranch_execz .LBB0_3154
	v_add_co_u32_e32 v46, vcc, 0x2000, v2
	s_nop 1
	v_addc_co_u32_e32 v47, vcc, 0, v3, vcc
	global_load_dword v45, v[46:47], off offset:1536
.LBB0_3154:
	s_or_b64 exec, exec, s[0:1]
	v_add_u32_e32 v46, 0x9c0, v54
	v_cmp_ge_i32_e32 vcc, s61, v46
	s_and_saveexec_b64 s[0:1], vcc
	s_cbranch_execz .LBB0_3156
	v_add_co_u32_e32 v46, vcc, 0x2000, v2
	s_nop 1
	v_addc_co_u32_e32 v47, vcc, 0, v3, vcc
	global_load_dword v44, v[46:47], off offset:1792
.LBB0_3156:
	s_or_b64 exec, exec, s[0:1]
	v_add_u32_e32 v46, 0xa00, v54
	v_cmp_ge_i32_e32 vcc, s61, v46
	v_mov_b32_e32 v46, 0
	v_mov_b32_e32 v47, 0
	s_and_saveexec_b64 s[0:1], vcc
	s_cbranch_execz .LBB0_3158
	v_add_co_u32_e32 v48, vcc, 0x2000, v2
	s_nop 1
	v_addc_co_u32_e32 v49, vcc, 0, v3, vcc
	global_load_dword v47, v[48:49], off offset:2048
.LBB0_3158:
	s_or_b64 exec, exec, s[0:1]
	v_add_u32_e32 v48, 0xa40, v54
	v_cmp_ge_i32_e32 vcc, s61, v48
	s_and_saveexec_b64 s[0:1], vcc
	s_cbranch_execz .LBB0_3160
	v_add_co_u32_e32 v48, vcc, 0x2000, v2
	s_nop 1
	v_addc_co_u32_e32 v49, vcc, 0, v3, vcc
	global_load_dword v46, v[48:49], off offset:2304
.LBB0_3160:
	s_or_b64 exec, exec, s[0:1]
	v_add_u32_e32 v48, 0xa80, v54
	v_cmp_ge_i32_e32 vcc, s61, v48
	v_mov_b32_e32 v48, 0
	v_mov_b32_e32 v49, 0
	s_and_saveexec_b64 s[0:1], vcc
	s_cbranch_execz .LBB0_3162
	v_add_co_u32_e32 v50, vcc, 0x2000, v2
	s_nop 1
	v_addc_co_u32_e32 v51, vcc, 0, v3, vcc
	global_load_dword v49, v[50:51], off offset:2560
.LBB0_3162:
	s_or_b64 exec, exec, s[0:1]
	v_add_u32_e32 v50, 0xac0, v54
	v_cmp_ge_i32_e32 vcc, s61, v50
	s_and_saveexec_b64 s[0:1], vcc
	s_cbranch_execz .LBB0_3164
	v_add_co_u32_e32 v50, vcc, 0x2000, v2
	s_nop 1
	v_addc_co_u32_e32 v51, vcc, 0, v3, vcc
	global_load_dword v48, v[50:51], off offset:2816
.LBB0_3164:
	s_or_b64 exec, exec, s[0:1]
	v_add_u32_e32 v50, 0xb00, v54
	v_cmp_ge_i32_e32 vcc, s61, v50
	v_mov_b32_e32 v50, 0
	v_mov_b32_e32 v51, 0
	s_and_saveexec_b64 s[0:1], vcc
	s_cbranch_execz .LBB0_3166
	v_add_co_u32_e32 v52, vcc, 0x2000, v2
	s_nop 1
	v_addc_co_u32_e32 v53, vcc, 0, v3, vcc
	global_load_dword v51, v[52:53], off offset:3072
.LBB0_3166:
	s_or_b64 exec, exec, s[0:1]
	v_add_u32_e32 v52, 0xb40, v54
	v_cmp_ge_i32_e32 vcc, s61, v52
	s_and_saveexec_b64 s[0:1], vcc
	s_cbranch_execz .LBB0_3168
	v_add_co_u32_e32 v52, vcc, 0x2000, v2
	s_nop 1
	v_addc_co_u32_e32 v53, vcc, 0, v3, vcc
	global_load_dword v50, v[52:53], off offset:3328
.LBB0_3168:
	s_or_b64 exec, exec, s[0:1]
	v_add_u32_e32 v52, 0xb80, v54
	v_cmp_ge_i32_e32 vcc, s61, v52
	v_mov_b32_e32 v52, 0
	v_mov_b32_e32 v53, 0
	s_and_saveexec_b64 s[0:1], vcc
	s_cbranch_execz .LBB0_3170
	v_add_co_u32_e32 v56, vcc, 0x2000, v2
	s_nop 1
	v_addc_co_u32_e32 v57, vcc, 0, v3, vcc
	global_load_dword v53, v[56:57], off offset:3584
.LBB0_3170:
	s_or_b64 exec, exec, s[0:1]
	v_add_u32_e32 v54, 0xbc0, v54
	v_cmp_ge_i32_e32 vcc, s61, v54
	s_and_saveexec_b64 s[0:1], vcc
	s_cbranch_execz .LBB0_3172
	v_add_co_u32_e32 v54, vcc, 0x2000, v2
	s_nop 1
	v_addc_co_u32_e32 v55, vcc, 0, v3, vcc
	global_load_dword v52, v[54:55], off offset:3840

.LBB0_3173:
	s_cmpk_lt_u32 s61, 0xfff
	s_mov_b64 s[0:1], -1
	s_cbranch_scc1 .LBB0_3175
	v_add_co_u32_e32 v70, vcc, 0x3000, v2
	s_mov_b64 s[0:1], 0
	v_addc_co_u32_e32 v71, vcc, 0, v3, vcc
	global_load_dword v55, v[70:71], off
	global_load_dword v54, v[70:71], off offset:256
	global_load_dword v57, v[70:71], off offset:512
	global_load_dword v56, v[70:71], off offset:768
	global_load_dword v59, v[70:71], off offset:1024
	global_load_dword v58, v[70:71], off offset:1280
	global_load_dword v61, v[70:71], off offset:1536
	global_load_dword v60, v[70:71], off offset:1792
	global_load_dword v63, v[70:71], off offset:2048
	global_load_dword v62, v[70:71], off offset:2304
	global_load_dword v65, v[70:71], off offset:2560
	global_load_dword v64, v[70:71], off offset:2816
	global_load_dword v67, v[70:71], off offset:3072
	global_load_dword v66, v[70:71], off offset:3328
	global_load_dword v69, v[70:71], off offset:3584
	global_load_dword v68, v[70:71], off offset:3840
.LBB0_3175:
	s_andn2_b64 vcc, exec, s[0:1]
	s_cbranch_vccnz .LBB0_3210
	v_mov_b32_e32 v55, 0
	s_cmpk_lt_u32 s61, 0xc00
	v_mov_b32_e32 v54, 0
	v_mov_b32_e32 v57, 0
	v_mov_b32_e32 v56, 0
	v_mov_b32_e32 v59, 0
	v_mov_b32_e32 v58, 0
	v_mov_b32_e32 v61, 0
	v_mov_b32_e32 v60, 0
	v_mov_b32_e32 v63, 0
	v_mov_b32_e32 v62, 0
	v_mov_b32_e32 v65, 0
	v_mov_b32_e32 v64, 0
	v_mov_b32_e32 v67, 0
	v_mov_b32_e32 v66, 0
	v_mov_b32_e32 v69, 0
	v_mov_b32_e32 v68, 0
	s_cbranch_scc1 .LBB0_3210
	v_mov_b32_e32 v70, v30
	v_mov_b32_e32 v55, 0
	v_add_u32_e32 v54, 0xc00, v70
	v_cmp_ge_i32_e32 vcc, s61, v54
	v_mov_b32_e32 v54, 0
	s_and_saveexec_b64 s[0:1], vcc
	s_cbranch_execz .LBB0_3179
	v_add_co_u32_e32 v56, vcc, 0x3000, v2
	s_nop 1
	v_addc_co_u32_e32 v57, vcc, 0, v3, vcc
	global_load_dword v55, v[56:57], off
.LBB0_3179:
	s_or_b64 exec, exec, s[0:1]
	v_add_u32_e32 v56, 0xc40, v70
	v_cmp_ge_i32_e32 vcc, s61, v56
	s_and_saveexec_b64 s[0:1], vcc
	s_cbranch_execz .LBB0_3181
	v_add_co_u32_e32 v56, vcc, 0x3000, v2
	s_nop 1
	v_addc_co_u32_e32 v57, vcc, 0, v3, vcc
	global_load_dword v54, v[56:57], off offset:256
.LBB0_3181:
	s_or_b64 exec, exec, s[0:1]
	v_add_u32_e32 v56, 0xc80, v70
	v_cmp_ge_i32_e32 vcc, s61, v56
	v_mov_b32_e32 v56, 0
	v_mov_b32_e32 v57, 0
	s_and_saveexec_b64 s[0:1], vcc
	s_cbranch_execz .LBB0_3183
	v_add_co_u32_e32 v58, vcc, 0x3000, v2
	s_nop 1
	v_addc_co_u32_e32 v59, vcc, 0, v3, vcc
	global_load_dword v57, v[58:59], off offset:512
.LBB0_3183:
	s_or_b64 exec, exec, s[0:1]
	v_add_u32_e32 v58, 0xcc0, v70
	v_cmp_ge_i32_e32 vcc, s61, v58
	s_and_saveexec_b64 s[0:1], vcc
	s_cbranch_execz .LBB0_3185
	v_add_co_u32_e32 v58, vcc, 0x3000, v2
	s_nop 1
	v_addc_co_u32_e32 v59, vcc, 0, v3, vcc
	global_load_dword v56, v[58:59], off offset:768
.LBB0_3185:
	s_or_b64 exec, exec, s[0:1]
	v_add_u32_e32 v58, 0xd00, v70
	v_cmp_ge_i32_e32 vcc, s61, v58
	v_mov_b32_e32 v58, 0
	v_mov_b32_e32 v59, 0
	s_and_saveexec_b64 s[0:1], vcc
	s_cbranch_execz .LBB0_3187
	v_add_co_u32_e32 v60, vcc, 0x3000, v2
	s_nop 1
	v_addc_co_u32_e32 v61, vcc, 0, v3, vcc
	global_load_dword v59, v[60:61], off offset:1024
.LBB0_3187:
	s_or_b64 exec, exec, s[0:1]
	v_add_u32_e32 v60, 0xd40, v70
	v_cmp_ge_i32_e32 vcc, s61, v60
	s_and_saveexec_b64 s[0:1], vcc
	s_cbranch_execz .LBB0_3189
	v_add_co_u32_e32 v60, vcc, 0x3000, v2
	s_nop 1
	v_addc_co_u32_e32 v61, vcc, 0, v3, vcc
	global_load_dword v58, v[60:61], off offset:1280
.LBB0_3189:
	s_or_b64 exec, exec, s[0:1]
	v_add_u32_e32 v60, 0xd80, v70
	v_cmp_ge_i32_e32 vcc, s61, v60
	v_mov_b32_e32 v60, 0
	v_mov_b32_e32 v61, 0
	s_and_saveexec_b64 s[0:1], vcc
	s_cbranch_execz .LBB0_3191
	v_add_co_u32_e32 v62, vcc, 0x3000, v2
	s_nop 1
	v_addc_co_u32_e32 v63, vcc, 0, v3, vcc
	global_load_dword v61, v[62:63], off offset:1536
.LBB0_3191:
	s_or_b64 exec, exec, s[0:1]
	v_add_u32_e32 v62, 0xdc0, v70
	v_cmp_ge_i32_e32 vcc, s61, v62
	s_and_saveexec_b64 s[0:1], vcc
	s_cbranch_execz .LBB0_3193
	v_add_co_u32_e32 v62, vcc, 0x3000, v2
	s_nop 1
	v_addc_co_u32_e32 v63, vcc, 0, v3, vcc
	global_load_dword v60, v[62:63], off offset:1792
.LBB0_3193:
	s_or_b64 exec, exec, s[0:1]
	v_add_u32_e32 v62, 0xe00, v70
	v_cmp_ge_i32_e32 vcc, s61, v62
	v_mov_b32_e32 v62, 0
	v_mov_b32_e32 v63, 0
	s_and_saveexec_b64 s[0:1], vcc
	s_cbranch_execz .LBB0_3195
	v_add_co_u32_e32 v64, vcc, 0x3000, v2
	s_nop 1
	v_addc_co_u32_e32 v65, vcc, 0, v3, vcc
	global_load_dword v63, v[64:65], off offset:2048
.LBB0_3195:
	s_or_b64 exec, exec, s[0:1]
	v_add_u32_e32 v64, 0xe40, v70
	v_cmp_ge_i32_e32 vcc, s61, v64
	s_and_saveexec_b64 s[0:1], vcc
	s_cbranch_execz .LBB0_3197
	v_add_co_u32_e32 v64, vcc, 0x3000, v2
	s_nop 1
	v_addc_co_u32_e32 v65, vcc, 0, v3, vcc
	global_load_dword v62, v[64:65], off offset:2304
.LBB0_3197:
	s_or_b64 exec, exec, s[0:1]
	v_add_u32_e32 v64, 0xe80, v70
	v_cmp_ge_i32_e32 vcc, s61, v64
	v_mov_b32_e32 v64, 0
	v_mov_b32_e32 v65, 0
	s_and_saveexec_b64 s[0:1], vcc
	s_cbranch_execz .LBB0_3199
	v_add_co_u32_e32 v66, vcc, 0x3000, v2
	s_nop 1
	v_addc_co_u32_e32 v67, vcc, 0, v3, vcc
	global_load_dword v65, v[66:67], off offset:2560
.LBB0_3199:
	s_or_b64 exec, exec, s[0:1]
	v_add_u32_e32 v66, 0xec0, v70
	v_cmp_ge_i32_e32 vcc, s61, v66
	s_and_saveexec_b64 s[0:1], vcc
	s_cbranch_execz .LBB0_3201
	v_add_co_u32_e32 v66, vcc, 0x3000, v2
	s_nop 1
	v_addc_co_u32_e32 v67, vcc, 0, v3, vcc
	global_load_dword v64, v[66:67], off offset:2816
.LBB0_3201:
	s_or_b64 exec, exec, s[0:1]
	v_add_u32_e32 v66, 0xf00, v70
	v_cmp_ge_i32_e32 vcc, s61, v66
	v_mov_b32_e32 v66, 0
	v_mov_b32_e32 v67, 0
	s_and_saveexec_b64 s[0:1], vcc
	s_cbranch_execz .LBB0_3203
	v_add_co_u32_e32 v68, vcc, 0x3000, v2
	s_nop 1
	v_addc_co_u32_e32 v69, vcc, 0, v3, vcc
	global_load_dword v67, v[68:69], off offset:3072
.LBB0_3203:
	s_or_b64 exec, exec, s[0:1]
	v_add_u32_e32 v68, 0xf40, v70
	v_cmp_ge_i32_e32 vcc, s61, v68
	s_and_saveexec_b64 s[0:1], vcc
	s_cbranch_execz .LBB0_3205
	v_add_co_u32_e32 v68, vcc, 0x3000, v2
	s_nop 1
	v_addc_co_u32_e32 v69, vcc, 0, v3, vcc
	global_load_dword v66, v[68:69], off offset:3328
.LBB0_3205:
	s_or_b64 exec, exec, s[0:1]
	v_add_u32_e32 v68, 0xf80, v70
	v_cmp_ge_i32_e32 vcc, s61, v68
	v_mov_b32_e32 v68, 0
	v_mov_b32_e32 v69, 0
	s_and_saveexec_b64 s[0:1], vcc
	s_cbranch_execz .LBB0_3207
	v_add_co_u32_e32 v72, vcc, 0x3000, v2
	s_nop 1
	v_addc_co_u32_e32 v73, vcc, 0, v3, vcc
	global_load_dword v69, v[72:73], off offset:3584
.LBB0_3207:
	s_or_b64 exec, exec, s[0:1]
	v_add_u32_e32 v70, 0xfc0, v70
	v_cmp_ge_i32_e32 vcc, s61, v70
	s_and_saveexec_b64 s[0:1], vcc
	s_cbranch_execz .LBB0_3209
	v_add_co_u32_e32 v70, vcc, 0x3000, v2
	s_nop 1
	v_addc_co_u32_e32 v71, vcc, 0, v3, vcc
	global_load_dword v68, v[70:71], off offset:3840

.LBB0_3210:
	s_cmpk_lt_u32 s61, 0x13ff
	s_mov_b64 s[0:1], -1
	s_cbranch_scc1 .LBB0_3212
	v_add_co_u32_e32 v86, vcc, 0x4000, v2
	s_mov_b64 s[0:1], 0
	s_nop 0
	v_addc_co_u32_e32 v87, vcc, 0, v3, vcc
	global_load_dword v71, v[86:87], off
	global_load_dword v70, v[86:87], off offset:256
	global_load_dword v73, v[86:87], off offset:512
	global_load_dword v72, v[86:87], off offset:768
	global_load_dword v75, v[86:87], off offset:1024
	global_load_dword v74, v[86:87], off offset:1280
	global_load_dword v77, v[86:87], off offset:1536
	global_load_dword v76, v[86:87], off offset:1792
	global_load_dword v79, v[86:87], off offset:2048
	global_load_dword v78, v[86:87], off offset:2304
	global_load_dword v81, v[86:87], off offset:2560
	global_load_dword v80, v[86:87], off offset:2816
	global_load_dword v83, v[86:87], off offset:3072
	global_load_dword v82, v[86:87], off offset:3328
	global_load_dword v85, v[86:87], off offset:3584
	global_load_dword v84, v[86:87], off offset:3840
.LBB0_3212:
	s_andn2_b64 vcc, exec, s[0:1]
	s_cbranch_vccnz .LBB0_3247
	v_mov_b32_e32 v71, 0
	s_cmpk_lt_u32 s61, 0x1000
	v_mov_b32_e32 v70, 0
	v_mov_b32_e32 v73, 0
	v_mov_b32_e32 v72, 0
	v_mov_b32_e32 v75, 0
	v_mov_b32_e32 v74, 0
	v_mov_b32_e32 v77, 0
	v_mov_b32_e32 v76, 0
	v_mov_b32_e32 v79, 0
	v_mov_b32_e32 v78, 0
	v_mov_b32_e32 v81, 0
	v_mov_b32_e32 v80, 0
	v_mov_b32_e32 v83, 0
	v_mov_b32_e32 v82, 0
	v_mov_b32_e32 v85, 0
	v_mov_b32_e32 v84, 0
	s_cbranch_scc1 .LBB0_3247
	v_mov_b32_e32 v86, v30
	v_mov_b32_e32 v71, 0
	v_add_u32_e32 v70, 0x1000, v86
	v_cmp_ge_i32_e32 vcc, s61, v70
	v_mov_b32_e32 v70, 0
	s_and_saveexec_b64 s[0:1], vcc
	s_cbranch_execz .LBB0_3216
	v_add_co_u32_e32 v72, vcc, 0x4000, v2
	s_nop 1
	v_addc_co_u32_e32 v73, vcc, 0, v3, vcc
	global_load_dword v71, v[72:73], off
.LBB0_3216:
	s_or_b64 exec, exec, s[0:1]
	v_add_u32_e32 v72, 0x1040, v86
	v_cmp_ge_i32_e32 vcc, s61, v72
	s_and_saveexec_b64 s[0:1], vcc
	s_cbranch_execz .LBB0_3218
	v_add_co_u32_e32 v72, vcc, 0x4000, v2
	s_nop 1
	v_addc_co_u32_e32 v73, vcc, 0, v3, vcc
	global_load_dword v70, v[72:73], off offset:256
.LBB0_3218:
	s_or_b64 exec, exec, s[0:1]
	v_add_u32_e32 v72, 0x1080, v86
	v_cmp_ge_i32_e32 vcc, s61, v72
	v_mov_b32_e32 v72, 0
	v_mov_b32_e32 v73, 0
	s_and_saveexec_b64 s[0:1], vcc
	s_cbranch_execz .LBB0_3220
	v_add_co_u32_e32 v74, vcc, 0x4000, v2
	s_nop 1
	v_addc_co_u32_e32 v75, vcc, 0, v3, vcc
	global_load_dword v73, v[74:75], off offset:512
.LBB0_3220:
	s_or_b64 exec, exec, s[0:1]
	v_add_u32_e32 v74, 0x10c0, v86
	v_cmp_ge_i32_e32 vcc, s61, v74
	s_and_saveexec_b64 s[0:1], vcc
	s_cbranch_execz .LBB0_3222
	v_add_co_u32_e32 v74, vcc, 0x4000, v2
	s_nop 1
	v_addc_co_u32_e32 v75, vcc, 0, v3, vcc
	global_load_dword v72, v[74:75], off offset:768
.LBB0_3222:
	s_or_b64 exec, exec, s[0:1]
	v_add_u32_e32 v74, 0x1100, v86
	v_cmp_ge_i32_e32 vcc, s61, v74
	v_mov_b32_e32 v74, 0
	v_mov_b32_e32 v75, 0
	s_and_saveexec_b64 s[0:1], vcc
	s_cbranch_execz .LBB0_3224
	v_add_co_u32_e32 v76, vcc, 0x4000, v2
	s_nop 1
	v_addc_co_u32_e32 v77, vcc, 0, v3, vcc
	global_load_dword v75, v[76:77], off offset:1024
.LBB0_3224:
	s_or_b64 exec, exec, s[0:1]
	v_add_u32_e32 v76, 0x1140, v86
	v_cmp_ge_i32_e32 vcc, s61, v76
	s_and_saveexec_b64 s[0:1], vcc
	s_cbranch_execz .LBB0_3226
	v_add_co_u32_e32 v76, vcc, 0x4000, v2
	s_nop 1
	v_addc_co_u32_e32 v77, vcc, 0, v3, vcc
	global_load_dword v74, v[76:77], off offset:1280
.LBB0_3226:
	s_or_b64 exec, exec, s[0:1]
	v_add_u32_e32 v76, 0x1180, v86
	v_cmp_ge_i32_e32 vcc, s61, v76
	v_mov_b32_e32 v76, 0
	v_mov_b32_e32 v77, 0
	s_and_saveexec_b64 s[0:1], vcc
	s_cbranch_execz .LBB0_3228
	v_add_co_u32_e32 v78, vcc, 0x4000, v2
	s_nop 1
	v_addc_co_u32_e32 v79, vcc, 0, v3, vcc
	global_load_dword v77, v[78:79], off offset:1536
.LBB0_3228:
	s_or_b64 exec, exec, s[0:1]
	v_add_u32_e32 v78, 0x11c0, v86
	v_cmp_ge_i32_e32 vcc, s61, v78
	s_and_saveexec_b64 s[0:1], vcc
	s_cbranch_execz .LBB0_3230
	v_add_co_u32_e32 v78, vcc, 0x4000, v2
	s_nop 1
	v_addc_co_u32_e32 v79, vcc, 0, v3, vcc
	global_load_dword v76, v[78:79], off offset:1792
.LBB0_3230:
	s_or_b64 exec, exec, s[0:1]
	v_add_u32_e32 v78, 0x1200, v86
	v_cmp_ge_i32_e32 vcc, s61, v78
	v_mov_b32_e32 v78, 0
	v_mov_b32_e32 v79, 0
	s_and_saveexec_b64 s[0:1], vcc
	s_cbranch_execz .LBB0_3232
	v_add_co_u32_e32 v80, vcc, 0x4000, v2
	s_nop 1
	v_addc_co_u32_e32 v81, vcc, 0, v3, vcc
	global_load_dword v79, v[80:81], off offset:2048
.LBB0_3232:
	s_or_b64 exec, exec, s[0:1]
	v_add_u32_e32 v80, 0x1240, v86
	v_cmp_ge_i32_e32 vcc, s61, v80
	s_and_saveexec_b64 s[0:1], vcc
	s_cbranch_execz .LBB0_3234
	v_add_co_u32_e32 v80, vcc, 0x4000, v2
	s_nop 1
	v_addc_co_u32_e32 v81, vcc, 0, v3, vcc
	global_load_dword v78, v[80:81], off offset:2304
.LBB0_3234:
	s_or_b64 exec, exec, s[0:1]
	v_add_u32_e32 v80, 0x1280, v86
	v_cmp_ge_i32_e32 vcc, s61, v80
	v_mov_b32_e32 v80, 0
	v_mov_b32_e32 v81, 0
	s_and_saveexec_b64 s[0:1], vcc
	s_cbranch_execz .LBB0_3236
	v_add_co_u32_e32 v82, vcc, 0x4000, v2
	s_nop 1
	v_addc_co_u32_e32 v83, vcc, 0, v3, vcc
	global_load_dword v81, v[82:83], off offset:2560
.LBB0_3236:
	s_or_b64 exec, exec, s[0:1]
	v_add_u32_e32 v82, 0x12c0, v86
	v_cmp_ge_i32_e32 vcc, s61, v82
	s_and_saveexec_b64 s[0:1], vcc
	s_cbranch_execz .LBB0_3238
	v_add_co_u32_e32 v82, vcc, 0x4000, v2
	s_nop 1
	v_addc_co_u32_e32 v83, vcc, 0, v3, vcc
	global_load_dword v80, v[82:83], off offset:2816
.LBB0_3238:
	s_or_b64 exec, exec, s[0:1]
	v_add_u32_e32 v82, 0x1300, v86
	v_cmp_ge_i32_e32 vcc, s61, v82
	v_mov_b32_e32 v82, 0
	v_mov_b32_e32 v83, 0
	s_and_saveexec_b64 s[0:1], vcc
	s_cbranch_execz .LBB0_3240
	v_add_co_u32_e32 v84, vcc, 0x4000, v2
	s_nop 1
	v_addc_co_u32_e32 v85, vcc, 0, v3, vcc
	global_load_dword v83, v[84:85], off offset:3072
.LBB0_3240:
	s_or_b64 exec, exec, s[0:1]
	v_add_u32_e32 v84, 0x1340, v86
	v_cmp_ge_i32_e32 vcc, s61, v84
	s_and_saveexec_b64 s[0:1], vcc
	s_cbranch_execz .LBB0_3242
	v_add_co_u32_e32 v84, vcc, 0x4000, v2
	s_nop 1
	v_addc_co_u32_e32 v85, vcc, 0, v3, vcc
	global_load_dword v82, v[84:85], off offset:3328
.LBB0_3242:
	s_or_b64 exec, exec, s[0:1]
	v_add_u32_e32 v84, 0x1380, v86
	v_cmp_ge_i32_e32 vcc, s61, v84
	v_mov_b32_e32 v84, 0
	v_mov_b32_e32 v85, 0
	s_and_saveexec_b64 s[0:1], vcc
	s_cbranch_execz .LBB0_3244
	v_add_co_u32_e32 v88, vcc, 0x4000, v2
	s_nop 1
	v_addc_co_u32_e32 v89, vcc, 0, v3, vcc
	global_load_dword v85, v[88:89], off offset:3584
.LBB0_3244:
	s_or_b64 exec, exec, s[0:1]
	v_add_u32_e32 v86, 0x13c0, v86
	v_cmp_ge_i32_e32 vcc, s61, v86
	s_and_saveexec_b64 s[0:1], vcc
	s_cbranch_execz .LBB0_3246
	v_add_co_u32_e32 v86, vcc, 0x4000, v2
	s_nop 1
	v_addc_co_u32_e32 v87, vcc, 0, v3, vcc
	global_load_dword v84, v[86:87], off offset:3840

.LBB0_3247:
	s_cmpk_lt_u32 s61, 0x17ff
	s_mov_b64 s[0:1], -1
	s_cbranch_scc1 .LBB0_3249
	v_add_co_u32_e32 v102, vcc, 0x5000, v2
	s_mov_b64 s[0:1], 0
	s_nop 0
	v_addc_co_u32_e32 v103, vcc, 0, v3, vcc
	global_load_dword v87, v[102:103], off
	global_load_dword v86, v[102:103], off offset:256
	global_load_dword v89, v[102:103], off offset:512
	global_load_dword v88, v[102:103], off offset:768
	global_load_dword v91, v[102:103], off offset:1024
	global_load_dword v90, v[102:103], off offset:1280
	global_load_dword v93, v[102:103], off offset:1536
	global_load_dword v92, v[102:103], off offset:1792
	global_load_dword v95, v[102:103], off offset:2048
	global_load_dword v94, v[102:103], off offset:2304
	global_load_dword v97, v[102:103], off offset:2560
	global_load_dword v96, v[102:103], off offset:2816
	global_load_dword v99, v[102:103], off offset:3072
	global_load_dword v98, v[102:103], off offset:3328
	global_load_dword v101, v[102:103], off offset:3584
	global_load_dword v100, v[102:103], off offset:3840
.LBB0_3249:
	s_andn2_b64 vcc, exec, s[0:1]
	s_cbranch_vccnz .LBB0_3284
	v_mov_b32_e32 v87, 0
	s_cmpk_lt_u32 s61, 0x1400
	v_mov_b32_e32 v86, 0
	v_mov_b32_e32 v89, 0
	v_mov_b32_e32 v88, 0
	v_mov_b32_e32 v91, 0
	v_mov_b32_e32 v90, 0
	v_mov_b32_e32 v93, 0
	v_mov_b32_e32 v92, 0
	v_mov_b32_e32 v95, 0
	v_mov_b32_e32 v94, 0
	v_mov_b32_e32 v97, 0
	v_mov_b32_e32 v96, 0
	v_mov_b32_e32 v99, 0
	v_mov_b32_e32 v98, 0
	v_mov_b32_e32 v101, 0
	v_mov_b32_e32 v100, 0
	s_cbranch_scc1 .LBB0_3284
	v_mov_b32_e32 v102, v30
	v_mov_b32_e32 v87, 0
	v_add_u32_e32 v86, 0x1400, v102
	v_cmp_ge_i32_e32 vcc, s61, v86
	v_mov_b32_e32 v86, 0
	s_and_saveexec_b64 s[0:1], vcc
	s_cbranch_execz .LBB0_3253
	v_add_co_u32_e32 v88, vcc, 0x5000, v2
	s_nop 1
	v_addc_co_u32_e32 v89, vcc, 0, v3, vcc
	global_load_dword v87, v[88:89], off
.LBB0_3253:
	s_or_b64 exec, exec, s[0:1]
	v_add_u32_e32 v88, 0x1440, v102
	v_cmp_ge_i32_e32 vcc, s61, v88
	s_and_saveexec_b64 s[0:1], vcc
	s_cbranch_execz .LBB0_3255
	v_add_co_u32_e32 v88, vcc, 0x5000, v2
	s_nop 1
	v_addc_co_u32_e32 v89, vcc, 0, v3, vcc
	global_load_dword v86, v[88:89], off offset:256
.LBB0_3255:
	s_or_b64 exec, exec, s[0:1]
	v_add_u32_e32 v88, 0x1480, v102
	v_cmp_ge_i32_e32 vcc, s61, v88
	v_mov_b32_e32 v88, 0
	v_mov_b32_e32 v89, 0
	s_and_saveexec_b64 s[0:1], vcc
	s_cbranch_execz .LBB0_3257
	v_add_co_u32_e32 v90, vcc, 0x5000, v2
	s_nop 1
	v_addc_co_u32_e32 v91, vcc, 0, v3, vcc
	global_load_dword v89, v[90:91], off offset:512
.LBB0_3257:
	s_or_b64 exec, exec, s[0:1]
	v_add_u32_e32 v90, 0x14c0, v102
	v_cmp_ge_i32_e32 vcc, s61, v90
	s_and_saveexec_b64 s[0:1], vcc
	s_cbranch_execz .LBB0_3259
	v_add_co_u32_e32 v90, vcc, 0x5000, v2
	s_nop 1
	v_addc_co_u32_e32 v91, vcc, 0, v3, vcc
	global_load_dword v88, v[90:91], off offset:768
.LBB0_3259:
	s_or_b64 exec, exec, s[0:1]
	v_add_u32_e32 v90, 0x1500, v102
	v_cmp_ge_i32_e32 vcc, s61, v90
	v_mov_b32_e32 v90, 0
	v_mov_b32_e32 v91, 0
	s_and_saveexec_b64 s[0:1], vcc
	s_cbranch_execz .LBB0_3261
	v_add_co_u32_e32 v92, vcc, 0x5000, v2
	s_nop 1
	v_addc_co_u32_e32 v93, vcc, 0, v3, vcc
	global_load_dword v91, v[92:93], off offset:1024
.LBB0_3261:
	s_or_b64 exec, exec, s[0:1]
	v_add_u32_e32 v92, 0x1540, v102
	v_cmp_ge_i32_e32 vcc, s61, v92
	s_and_saveexec_b64 s[0:1], vcc
	s_cbranch_execz .LBB0_3263
	v_add_co_u32_e32 v92, vcc, 0x5000, v2
	s_nop 1
	v_addc_co_u32_e32 v93, vcc, 0, v3, vcc
	global_load_dword v90, v[92:93], off offset:1280
.LBB0_3263:
	s_or_b64 exec, exec, s[0:1]
	v_add_u32_e32 v92, 0x1580, v102
	v_cmp_ge_i32_e32 vcc, s61, v92
	v_mov_b32_e32 v92, 0
	v_mov_b32_e32 v93, 0
	s_and_saveexec_b64 s[0:1], vcc
	s_cbranch_execz .LBB0_3265
	v_add_co_u32_e32 v94, vcc, 0x5000, v2
	s_nop 1
	v_addc_co_u32_e32 v95, vcc, 0, v3, vcc
	global_load_dword v93, v[94:95], off offset:1536
.LBB0_3265:
	s_or_b64 exec, exec, s[0:1]
	v_add_u32_e32 v94, 0x15c0, v102
	v_cmp_ge_i32_e32 vcc, s61, v94
	s_and_saveexec_b64 s[0:1], vcc
	s_cbranch_execz .LBB0_3267
	v_add_co_u32_e32 v94, vcc, 0x5000, v2
	s_nop 1
	v_addc_co_u32_e32 v95, vcc, 0, v3, vcc
	global_load_dword v92, v[94:95], off offset:1792
.LBB0_3267:
	s_or_b64 exec, exec, s[0:1]
	v_add_u32_e32 v94, 0x1600, v102
	v_cmp_ge_i32_e32 vcc, s61, v94
	v_mov_b32_e32 v94, 0
	v_mov_b32_e32 v95, 0
	s_and_saveexec_b64 s[0:1], vcc
	s_cbranch_execz .LBB0_3269
	v_add_co_u32_e32 v96, vcc, 0x5000, v2
	s_nop 1
	v_addc_co_u32_e32 v97, vcc, 0, v3, vcc
	global_load_dword v95, v[96:97], off offset:2048
.LBB0_3269:
	s_or_b64 exec, exec, s[0:1]
	v_add_u32_e32 v96, 0x1640, v102
	v_cmp_ge_i32_e32 vcc, s61, v96
	s_and_saveexec_b64 s[0:1], vcc
	s_cbranch_execz .LBB0_3271
	v_add_co_u32_e32 v96, vcc, 0x5000, v2
	s_nop 1
	v_addc_co_u32_e32 v97, vcc, 0, v3, vcc
	global_load_dword v94, v[96:97], off offset:2304
.LBB0_3271:
	s_or_b64 exec, exec, s[0:1]
	v_add_u32_e32 v96, 0x1680, v102
	v_cmp_ge_i32_e32 vcc, s61, v96
	v_mov_b32_e32 v96, 0
	v_mov_b32_e32 v97, 0
	s_and_saveexec_b64 s[0:1], vcc
	s_cbranch_execz .LBB0_3273
	v_add_co_u32_e32 v98, vcc, 0x5000, v2
	s_nop 1
	v_addc_co_u32_e32 v99, vcc, 0, v3, vcc
	global_load_dword v97, v[98:99], off offset:2560
.LBB0_3273:
	s_or_b64 exec, exec, s[0:1]
	v_add_u32_e32 v98, 0x16c0, v102
	v_cmp_ge_i32_e32 vcc, s61, v98
	s_and_saveexec_b64 s[0:1], vcc
	s_cbranch_execz .LBB0_3275
	v_add_co_u32_e32 v98, vcc, 0x5000, v2
	s_nop 1
	v_addc_co_u32_e32 v99, vcc, 0, v3, vcc
	global_load_dword v96, v[98:99], off offset:2816
.LBB0_3275:
	s_or_b64 exec, exec, s[0:1]
	v_add_u32_e32 v98, 0x1700, v102
	v_cmp_ge_i32_e32 vcc, s61, v98
	v_mov_b32_e32 v98, 0
	v_mov_b32_e32 v99, 0
	s_and_saveexec_b64 s[0:1], vcc
	s_cbranch_execz .LBB0_3277
	v_add_co_u32_e32 v100, vcc, 0x5000, v2
	s_nop 1
	v_addc_co_u32_e32 v101, vcc, 0, v3, vcc
	global_load_dword v99, v[100:101], off offset:3072
.LBB0_3277:
	s_or_b64 exec, exec, s[0:1]
	v_add_u32_e32 v100, 0x1740, v102
	v_cmp_ge_i32_e32 vcc, s61, v100
	s_and_saveexec_b64 s[0:1], vcc
	s_cbranch_execz .LBB0_3279
	v_add_co_u32_e32 v100, vcc, 0x5000, v2
	s_nop 1
	v_addc_co_u32_e32 v101, vcc, 0, v3, vcc
	global_load_dword v98, v[100:101], off offset:3328
.LBB0_3279:
	s_or_b64 exec, exec, s[0:1]
	v_add_u32_e32 v100, 0x1780, v102
	v_cmp_ge_i32_e32 vcc, s61, v100
	v_mov_b32_e32 v100, 0
	v_mov_b32_e32 v101, 0
	s_and_saveexec_b64 s[0:1], vcc
	s_cbranch_execz .LBB0_3281
	v_add_co_u32_e32 v104, vcc, 0x5000, v2
	s_nop 1
	v_addc_co_u32_e32 v105, vcc, 0, v3, vcc
	global_load_dword v101, v[104:105], off offset:3584
.LBB0_3281:
	s_or_b64 exec, exec, s[0:1]
	v_add_u32_e32 v102, 0x17c0, v102
	v_cmp_ge_i32_e32 vcc, s61, v102
	s_and_saveexec_b64 s[0:1], vcc
	s_cbranch_execz .LBB0_3283
	v_add_co_u32_e32 v102, vcc, 0x5000, v2
	s_nop 1
	v_addc_co_u32_e32 v103, vcc, 0, v3, vcc
	global_load_dword v100, v[102:103], off offset:3840

.LBB0_3284:
	s_cmpk_lt_u32 s61, 0x1bff
	s_mov_b64 s[0:1], -1
	s_cbranch_scc1 .LBB0_3286
	v_add_co_u32_e32 v118, vcc, 0x6000, v2
	s_mov_b64 s[0:1], 0
	s_nop 0
	v_addc_co_u32_e32 v119, vcc, 0, v3, vcc
	global_load_dword v103, v[118:119], off
	global_load_dword v102, v[118:119], off offset:256
	global_load_dword v105, v[118:119], off offset:512
	global_load_dword v104, v[118:119], off offset:768
	global_load_dword v107, v[118:119], off offset:1024
	global_load_dword v106, v[118:119], off offset:1280
	global_load_dword v109, v[118:119], off offset:1536
	global_load_dword v108, v[118:119], off offset:1792
	global_load_dword v111, v[118:119], off offset:2048
	global_load_dword v110, v[118:119], off offset:2304
	global_load_dword v113, v[118:119], off offset:2560
	global_load_dword v112, v[118:119], off offset:2816
	global_load_dword v115, v[118:119], off offset:3072
	global_load_dword v114, v[118:119], off offset:3328
	global_load_dword v117, v[118:119], off offset:3584
	global_load_dword v116, v[118:119], off offset:3840
.LBB0_3286:
	s_andn2_b64 vcc, exec, s[0:1]
	s_cbranch_vccnz .LBB0_3321
	v_mov_b32_e32 v103, 0
	s_cmpk_lt_u32 s61, 0x1800
	v_mov_b32_e32 v102, 0
	v_mov_b32_e32 v105, 0
	v_mov_b32_e32 v104, 0
	v_mov_b32_e32 v107, 0
	v_mov_b32_e32 v106, 0
	v_mov_b32_e32 v109, 0
	v_mov_b32_e32 v108, 0
	v_mov_b32_e32 v111, 0
	v_mov_b32_e32 v110, 0
	v_mov_b32_e32 v113, 0
	v_mov_b32_e32 v112, 0
	v_mov_b32_e32 v115, 0
	v_mov_b32_e32 v114, 0
	v_mov_b32_e32 v117, 0
	v_mov_b32_e32 v116, 0
	s_cbranch_scc1 .LBB0_3321
	v_mov_b32_e32 v118, v30
	v_mov_b32_e32 v103, 0
	v_add_u32_e32 v102, 0x1800, v118
	v_cmp_ge_i32_e32 vcc, s61, v102
	v_mov_b32_e32 v102, 0
	s_and_saveexec_b64 s[0:1], vcc
	s_cbranch_execz .LBB0_3290
	v_add_co_u32_e32 v104, vcc, 0x6000, v2
	s_nop 1
	v_addc_co_u32_e32 v105, vcc, 0, v3, vcc
	global_load_dword v103, v[104:105], off
.LBB0_3290:
	s_or_b64 exec, exec, s[0:1]
	v_add_u32_e32 v104, 0x1840, v118
	v_cmp_ge_i32_e32 vcc, s61, v104
	s_and_saveexec_b64 s[0:1], vcc
	s_cbranch_execz .LBB0_3292
	v_add_co_u32_e32 v104, vcc, 0x6000, v2
	s_nop 1
	v_addc_co_u32_e32 v105, vcc, 0, v3, vcc
	global_load_dword v102, v[104:105], off offset:256
.LBB0_3292:
	s_or_b64 exec, exec, s[0:1]
	v_add_u32_e32 v104, 0x1880, v118
	v_cmp_ge_i32_e32 vcc, s61, v104
	v_mov_b32_e32 v104, 0
	v_mov_b32_e32 v105, 0
	s_and_saveexec_b64 s[0:1], vcc
	s_cbranch_execz .LBB0_3294
	v_add_co_u32_e32 v106, vcc, 0x6000, v2
	s_nop 1
	v_addc_co_u32_e32 v107, vcc, 0, v3, vcc
	global_load_dword v105, v[106:107], off offset:512
.LBB0_3294:
	s_or_b64 exec, exec, s[0:1]
	v_add_u32_e32 v106, 0x18c0, v118
	v_cmp_ge_i32_e32 vcc, s61, v106
	s_and_saveexec_b64 s[0:1], vcc
	s_cbranch_execz .LBB0_3296
	v_add_co_u32_e32 v106, vcc, 0x6000, v2
	s_nop 1
	v_addc_co_u32_e32 v107, vcc, 0, v3, vcc
	global_load_dword v104, v[106:107], off offset:768
.LBB0_3296:
	s_or_b64 exec, exec, s[0:1]
	v_add_u32_e32 v106, 0x1900, v118
	v_cmp_ge_i32_e32 vcc, s61, v106
	v_mov_b32_e32 v106, 0
	v_mov_b32_e32 v107, 0
	s_and_saveexec_b64 s[0:1], vcc
	s_cbranch_execz .LBB0_3298
	v_add_co_u32_e32 v108, vcc, 0x6000, v2
	s_nop 1
	v_addc_co_u32_e32 v109, vcc, 0, v3, vcc
	global_load_dword v107, v[108:109], off offset:1024
.LBB0_3298:
	s_or_b64 exec, exec, s[0:1]
	v_add_u32_e32 v108, 0x1940, v118
	v_cmp_ge_i32_e32 vcc, s61, v108
	s_and_saveexec_b64 s[0:1], vcc
	s_cbranch_execz .LBB0_3300
	v_add_co_u32_e32 v108, vcc, 0x6000, v2
	s_nop 1
	v_addc_co_u32_e32 v109, vcc, 0, v3, vcc
	global_load_dword v106, v[108:109], off offset:1280
.LBB0_3300:
	s_or_b64 exec, exec, s[0:1]
	v_add_u32_e32 v108, 0x1980, v118
	v_cmp_ge_i32_e32 vcc, s61, v108
	v_mov_b32_e32 v108, 0
	v_mov_b32_e32 v109, 0
	s_and_saveexec_b64 s[0:1], vcc
	s_cbranch_execz .LBB0_3302
	v_add_co_u32_e32 v110, vcc, 0x6000, v2
	s_nop 1
	v_addc_co_u32_e32 v111, vcc, 0, v3, vcc
	global_load_dword v109, v[110:111], off offset:1536
.LBB0_3302:
	s_or_b64 exec, exec, s[0:1]
	v_add_u32_e32 v110, 0x19c0, v118
	v_cmp_ge_i32_e32 vcc, s61, v110
	s_and_saveexec_b64 s[0:1], vcc
	s_cbranch_execz .LBB0_3304
	v_add_co_u32_e32 v110, vcc, 0x6000, v2
	s_nop 1
	v_addc_co_u32_e32 v111, vcc, 0, v3, vcc
	global_load_dword v108, v[110:111], off offset:1792
.LBB0_3304:
	s_or_b64 exec, exec, s[0:1]
	v_add_u32_e32 v110, 0x1a00, v118
	v_cmp_ge_i32_e32 vcc, s61, v110
	v_mov_b32_e32 v110, 0
	v_mov_b32_e32 v111, 0
	s_and_saveexec_b64 s[0:1], vcc
	s_cbranch_execz .LBB0_3306
	v_add_co_u32_e32 v112, vcc, 0x6000, v2
	s_nop 1
	v_addc_co_u32_e32 v113, vcc, 0, v3, vcc
	global_load_dword v111, v[112:113], off offset:2048
.LBB0_3306:
	s_or_b64 exec, exec, s[0:1]
	v_add_u32_e32 v112, 0x1a40, v118
	v_cmp_ge_i32_e32 vcc, s61, v112
	s_and_saveexec_b64 s[0:1], vcc
	s_cbranch_execz .LBB0_3308
	v_add_co_u32_e32 v112, vcc, 0x6000, v2
	s_nop 1
	v_addc_co_u32_e32 v113, vcc, 0, v3, vcc
	global_load_dword v110, v[112:113], off offset:2304
.LBB0_3308:
	s_or_b64 exec, exec, s[0:1]
	v_add_u32_e32 v112, 0x1a80, v118
	v_cmp_ge_i32_e32 vcc, s61, v112
	v_mov_b32_e32 v112, 0
	v_mov_b32_e32 v113, 0
	s_and_saveexec_b64 s[0:1], vcc
	s_cbranch_execz .LBB0_3310
	v_add_co_u32_e32 v114, vcc, 0x6000, v2
	s_nop 1
	v_addc_co_u32_e32 v115, vcc, 0, v3, vcc
	global_load_dword v113, v[114:115], off offset:2560
.LBB0_3310:
	s_or_b64 exec, exec, s[0:1]
	v_add_u32_e32 v114, 0x1ac0, v118
	v_cmp_ge_i32_e32 vcc, s61, v114
	s_and_saveexec_b64 s[0:1], vcc
	s_cbranch_execz .LBB0_3312
	v_add_co_u32_e32 v114, vcc, 0x6000, v2
	s_nop 1
	v_addc_co_u32_e32 v115, vcc, 0, v3, vcc
	global_load_dword v112, v[114:115], off offset:2816
.LBB0_3312:
	s_or_b64 exec, exec, s[0:1]
	v_add_u32_e32 v114, 0x1b00, v118
	v_cmp_ge_i32_e32 vcc, s61, v114
	v_mov_b32_e32 v114, 0
	v_mov_b32_e32 v115, 0
	s_and_saveexec_b64 s[0:1], vcc
	s_cbranch_execz .LBB0_3314
	v_add_co_u32_e32 v116, vcc, 0x6000, v2
	s_nop 1
	v_addc_co_u32_e32 v117, vcc, 0, v3, vcc
	global_load_dword v115, v[116:117], off offset:3072
.LBB0_3314:
	s_or_b64 exec, exec, s[0:1]
	v_add_u32_e32 v116, 0x1b40, v118
	v_cmp_ge_i32_e32 vcc, s61, v116
	s_and_saveexec_b64 s[0:1], vcc
	s_cbranch_execz .LBB0_3316
	v_add_co_u32_e32 v116, vcc, 0x6000, v2
	s_nop 1
	v_addc_co_u32_e32 v117, vcc, 0, v3, vcc
	global_load_dword v114, v[116:117], off offset:3328
.LBB0_3316:
	s_or_b64 exec, exec, s[0:1]
	v_add_u32_e32 v116, 0x1b80, v118
	v_cmp_ge_i32_e32 vcc, s61, v116
	v_mov_b32_e32 v116, 0
	v_mov_b32_e32 v117, 0
	s_and_saveexec_b64 s[0:1], vcc
	s_cbranch_execz .LBB0_3318
	v_add_co_u32_e32 v120, vcc, 0x6000, v2
	s_nop 1
	v_addc_co_u32_e32 v121, vcc, 0, v3, vcc
	global_load_dword v117, v[120:121], off offset:3584
.LBB0_3318:
	s_or_b64 exec, exec, s[0:1]
	v_add_u32_e32 v118, 0x1bc0, v118
	v_cmp_ge_i32_e32 vcc, s61, v118
	s_and_saveexec_b64 s[0:1], vcc
	s_cbranch_execz .LBB0_3320
	v_add_co_u32_e32 v118, vcc, 0x6000, v2
	s_nop 1
	v_addc_co_u32_e32 v119, vcc, 0, v3, vcc
	global_load_dword v116, v[118:119], off offset:3840

.LBB0_3321:
	s_cmpk_lt_u32 s61, 0x1fff
	s_mov_b64 s[0:1], -1
	s_cbranch_scc1 .LBB0_3323
	v_add_co_u32_e32 v134, vcc, 0x7000, v2
	s_mov_b64 s[0:1], 0
	s_nop 0
	v_addc_co_u32_e32 v135, vcc, 0, v3, vcc
	global_load_dword v119, v[134:135], off
	global_load_dword v118, v[134:135], off offset:256
	global_load_dword v123, v[134:135], off offset:512
	global_load_dword v120, v[134:135], off offset:768
	global_load_dword v125, v[134:135], off offset:1024
	global_load_dword v121, v[134:135], off offset:1280
	global_load_dword v127, v[134:135], off offset:1536
	global_load_dword v122, v[134:135], off offset:1792
	global_load_dword v129, v[134:135], off offset:2048
	global_load_dword v124, v[134:135], off offset:2304
	global_load_dword v131, v[134:135], off offset:2560
	global_load_dword v126, v[134:135], off offset:2816
	global_load_dword v132, v[134:135], off offset:3072
	global_load_dword v128, v[134:135], off offset:3328
	global_load_dword v133, v[134:135], off offset:3584
	global_load_dword v130, v[134:135], off offset:3840
.LBB0_3323:
	s_andn2_b64 vcc, exec, s[0:1]
	s_cbranch_vccnz .LBB0_3358
	v_mov_b32_e32 v130, 0
	s_cmpk_lt_u32 s61, 0x1c00
	v_mov_b32_e32 v133, 0
	v_mov_b32_e32 v128, 0
	v_mov_b32_e32 v132, 0
	v_mov_b32_e32 v126, 0
	v_mov_b32_e32 v131, 0
	v_mov_b32_e32 v124, 0
	v_mov_b32_e32 v129, 0
	v_mov_b32_e32 v122, 0
	v_mov_b32_e32 v127, 0
	v_mov_b32_e32 v121, 0
	v_mov_b32_e32 v125, 0
	v_mov_b32_e32 v119, 0
	v_mov_b32_e32 v118, 0
	v_mov_b32_e32 v123, 0
	v_mov_b32_e32 v120, 0
	s_cbranch_scc1 .LBB0_3358
	v_mov_b32_e32 v134, v30
	v_mov_b32_e32 v119, 0
	v_add_u32_e32 v118, 0x1c00, v134
	v_cmp_ge_i32_e32 vcc, s61, v118
	v_mov_b32_e32 v118, 0
	s_and_saveexec_b64 s[0:1], vcc
	s_cbranch_execz .LBB0_3327
	v_add_co_u32_e32 v120, vcc, 0x7000, v2
	s_nop 1
	v_addc_co_u32_e32 v121, vcc, 0, v3, vcc
	global_load_dword v119, v[120:121], off
.LBB0_3327:
	s_or_b64 exec, exec, s[0:1]
	v_add_u32_e32 v120, 0x1c40, v134
	v_cmp_ge_i32_e32 vcc, s61, v120
	s_and_saveexec_b64 s[0:1], vcc
	s_cbranch_execz .LBB0_3329
	v_add_co_u32_e32 v120, vcc, 0x7000, v2
	s_nop 1
	v_addc_co_u32_e32 v121, vcc, 0, v3, vcc
	global_load_dword v118, v[120:121], off offset:256
.LBB0_3329:
	s_or_b64 exec, exec, s[0:1]
	v_add_u32_e32 v120, 0x1c80, v134
	v_cmp_ge_i32_e32 vcc, s61, v120
	v_mov_b32_e32 v120, 0
	v_mov_b32_e32 v123, 0
	s_and_saveexec_b64 s[0:1], vcc
	s_cbranch_execz .LBB0_3331
	v_add_co_u32_e32 v122, vcc, 0x7000, v2
	s_nop 1
	v_addc_co_u32_e32 v123, vcc, 0, v3, vcc
	global_load_dword v123, v[122:123], off offset:512
.LBB0_3331:
	s_or_b64 exec, exec, s[0:1]
	v_add_u32_e32 v121, 0x1cc0, v134
	v_cmp_ge_i32_e32 vcc, s61, v121
	s_and_saveexec_b64 s[0:1], vcc
	s_cbranch_execz .LBB0_3333
	v_add_co_u32_e32 v120, vcc, 0x7000, v2
	s_nop 1
	v_addc_co_u32_e32 v121, vcc, 0, v3, vcc
	global_load_dword v120, v[120:121], off offset:768
.LBB0_3333:
	s_or_b64 exec, exec, s[0:1]
	v_add_u32_e32 v121, 0x1d00, v134
	v_cmp_ge_i32_e32 vcc, s61, v121
	v_mov_b32_e32 v121, 0
	v_mov_b32_e32 v125, 0
	s_and_saveexec_b64 s[0:1], vcc
	s_cbranch_execz .LBB0_3335
	v_add_co_u32_e32 v124, vcc, 0x7000, v2
	s_nop 1
	v_addc_co_u32_e32 v125, vcc, 0, v3, vcc
	global_load_dword v125, v[124:125], off offset:1024
.LBB0_3335:
	s_or_b64 exec, exec, s[0:1]
	v_add_u32_e32 v122, 0x1d40, v134
	v_cmp_ge_i32_e32 vcc, s61, v122
	s_and_saveexec_b64 s[0:1], vcc
	s_cbranch_execz .LBB0_3337
	v_add_co_u32_e32 v126, vcc, 0x7000, v2
	s_nop 1
	v_addc_co_u32_e32 v127, vcc, 0, v3, vcc
	global_load_dword v121, v[126:127], off offset:1280
.LBB0_3337:
	s_or_b64 exec, exec, s[0:1]
	v_add_u32_e32 v122, 0x1d80, v134
	v_cmp_ge_i32_e32 vcc, s61, v122
	v_mov_b32_e32 v122, 0
	v_mov_b32_e32 v127, 0
	s_and_saveexec_b64 s[0:1], vcc
	s_cbranch_execz .LBB0_3339
	v_add_co_u32_e32 v126, vcc, 0x7000, v2
	s_nop 1
	v_addc_co_u32_e32 v127, vcc, 0, v3, vcc
	global_load_dword v127, v[126:127], off offset:1536
.LBB0_3339:
	s_or_b64 exec, exec, s[0:1]
	v_add_u32_e32 v124, 0x1dc0, v134
	v_cmp_ge_i32_e32 vcc, s61, v124
	s_and_saveexec_b64 s[0:1], vcc
	s_cbranch_execz .LBB0_3341
	v_add_co_u32_e32 v128, vcc, 0x7000, v2
	s_nop 1
	v_addc_co_u32_e32 v129, vcc, 0, v3, vcc
	global_load_dword v122, v[128:129], off offset:1792
.LBB0_3341:
	s_or_b64 exec, exec, s[0:1]
	v_add_u32_e32 v124, 0x1e00, v134
	v_cmp_ge_i32_e32 vcc, s61, v124
	v_mov_b32_e32 v124, 0
	v_mov_b32_e32 v129, 0
	s_and_saveexec_b64 s[0:1], vcc
	s_cbranch_execz .LBB0_3343
	v_add_co_u32_e32 v128, vcc, 0x7000, v2
	s_nop 1
	v_addc_co_u32_e32 v129, vcc, 0, v3, vcc
	global_load_dword v129, v[128:129], off offset:2048
.LBB0_3343:
	s_or_b64 exec, exec, s[0:1]
	v_add_u32_e32 v126, 0x1e40, v134
	v_cmp_ge_i32_e32 vcc, s61, v126
	s_and_saveexec_b64 s[0:1], vcc
	s_cbranch_execz .LBB0_3345
	v_add_co_u32_e32 v130, vcc, 0x7000, v2
	s_nop 1
	v_addc_co_u32_e32 v131, vcc, 0, v3, vcc
	global_load_dword v124, v[130:131], off offset:2304
.LBB0_3345:
	s_or_b64 exec, exec, s[0:1]
	v_add_u32_e32 v126, 0x1e80, v134
	v_cmp_ge_i32_e32 vcc, s61, v126
	v_mov_b32_e32 v126, 0
	v_mov_b32_e32 v131, 0
	s_and_saveexec_b64 s[0:1], vcc
	s_cbranch_execz .LBB0_3347
	v_add_co_u32_e32 v130, vcc, 0x7000, v2
	s_nop 1
	v_addc_co_u32_e32 v131, vcc, 0, v3, vcc
	global_load_dword v131, v[130:131], off offset:2560
.LBB0_3347:
	s_or_b64 exec, exec, s[0:1]
	v_add_u32_e32 v128, 0x1ec0, v134
	v_cmp_ge_i32_e32 vcc, s61, v128
	s_and_saveexec_b64 s[0:1], vcc
	s_cbranch_execz .LBB0_3349
	v_add_co_u32_e32 v132, vcc, 0x7000, v2
	s_nop 1
	v_addc_co_u32_e32 v133, vcc, 0, v3, vcc
	global_load_dword v126, v[132:133], off offset:2816
.LBB0_3349:
	s_or_b64 exec, exec, s[0:1]
	v_add_u32_e32 v128, 0x1f00, v134
	v_cmp_ge_i32_e32 vcc, s61, v128
	v_mov_b32_e32 v128, 0
	v_mov_b32_e32 v132, 0
	s_and_saveexec_b64 s[0:1], vcc
	s_cbranch_execz .LBB0_3351
	v_add_co_u32_e32 v132, vcc, 0x7000, v2
	s_nop 1
	v_addc_co_u32_e32 v133, vcc, 0, v3, vcc
	global_load_dword v132, v[132:133], off offset:3072
.LBB0_3351:
	s_or_b64 exec, exec, s[0:1]
	v_add_u32_e32 v130, 0x1f40, v134
	v_cmp_ge_i32_e32 vcc, s61, v130
	s_and_saveexec_b64 s[0:1], vcc
	s_cbranch_execz .LBB0_3353
	v_add_co_u32_e32 v136, vcc, 0x7000, v2
	s_nop 1
	v_addc_co_u32_e32 v137, vcc, 0, v3, vcc
	global_load_dword v128, v[136:137], off offset:3328
.LBB0_3353:
	s_or_b64 exec, exec, s[0:1]
	v_add_u32_e32 v130, 0x1f80, v134
	v_cmp_ge_i32_e32 vcc, s61, v130
	v_mov_b32_e32 v130, 0
	v_mov_b32_e32 v133, 0
	s_and_saveexec_b64 s[0:1], vcc
	s_cbranch_execz .LBB0_3355
	v_add_co_u32_e32 v136, vcc, 0x7000, v2
	s_nop 1
	v_addc_co_u32_e32 v137, vcc, 0, v3, vcc
	global_load_dword v133, v[136:137], off offset:3584
.LBB0_3355:
	s_or_b64 exec, exec, s[0:1]
	v_add_u32_e32 v134, 0x1fc0, v134
	v_cmp_ge_i32_e32 vcc, s61, v134
	s_and_saveexec_b64 s[0:1], vcc
	s_cbranch_execz .LBB0_3357
	v_add_co_u32_e32 v2, vcc, 0x7000, v2
	s_nop 1
	v_addc_co_u32_e32 v3, vcc, 0, v3, vcc
	global_load_dword v130, v[2:3], off offset:3840
